# P1 epilogue (v/gates rewritten, q/k patched): lane-pair swap so each store writes 8 rows x 128B full lines instead of 16 rows x 64B
# speedup vs baseline: 1.0366x; 1.0220x over previous
; __device__ __forceinline__ unsigned cvt_pk_bf16(float lo, float hi) { unsigned r; asm volatile("v_cvt_pk_bf16_f32 %0, %1, %2" : "=v"(r) : "v"(lo), "v"(hi)); return r; }
; __device__ __forceinline__ float silu_f(float x) { return x * __builtin_amdgcn_rcpf(1.f + __expf(-x)); }
;     __device__ __forceinline__ void operator()(const f32x4 (&acc)[2][2][4][2], const pg8::Unit& u, int wr, int wc, int fr, int fq) const {
;     ...
;         } else {
;             const bool act = (sec == 3 || sec == 7);
;             const int col0 = 256 * half + 64 * wc + 8 * fq;
; #pragma unroll
;             for (int ai = 0; ai < 2; ++ai)
; #pragma unroll
;                 for (int m = 0; m < 4; ++m) {
;                     bf16_t* rowp = base + (size_t)(row0 + ai * 128 + m * 16) * 512 + col0;
; #pragma unroll
;                     for (int bj = 0; bj < 2; ++bj) { f32x4 v0 = acc[ai][bj][m][0], v1 = acc[ai][bj][m][1];
;                         if (act) { v0 = (f32x4){silu_f(v0[0]), silu_f(v0[1]), silu_f(v0[2]), silu_f(v0[3])}; v1 = (f32x4){silu_f(v1[0]), silu_f(v1[1]), silu_f(v1[2]), silu_f(v1[3])}; }
;                         u32x4 w; w.x = cvt_pk_bf16(v0[0], v0[1]); w.y = cvt_pk_bf16(v0[2], v0[3]); w.z = cvt_pk_bf16(v1[0], v1[1]); w.w = cvt_pk_bf16(v1[2], v1[3]);
;                         *(u32x4*)(rowp + 32 * bj) = w; }
;                 }
.LBB0_168:
	s_and_b32 s4, s41, 0x7ffffffe
	s_cmp_lg_u32 s4, 4
	s_mov_b64 s[4:5], -1
	s_cbranch_scc0 .LBB0_202
	s_and_b32 s4, s41, 0x7ffffffb
	v_lshlrev_b32_e32 v130, 1, v182
	v_lshl_or_b32 v154, s27, 9, v130
	v_and_b32_e32 v131, 1, v172
	v_lshl_add_u32 v154, v131, 6, v154
	v_and_b32_e32 v132, -2, v172
	v_ashrrev_i32_e32 v173, 31, v172
	v_ashrrev_i32_e32 v133, 31, v132
	v_lshlrev_b64 v[132:133], 10, v[132:133]
	v_lshl_add_u64 v[130:131], s[48:49], 0, v[154:155]
	v_lshl_add_u64 v[130:131], v[130:131], 0, v[132:133]
	s_mov_b32 vcc_lo, 0x55555555
	s_mov_b32 vcc_hi, 0x55555555
	s_cmp_lg_u32 s4, 3
	s_mov_b64 s[4:5], 0x4000
	s_cbranch_scc1 .Lp1e_plain
	v_mul_f32_e32 v224, 0xbfb8aa3b, v118
	v_mul_f32_e32 v225, 0xbfb8aa3b, v119
	v_mul_f32_e32 v226, 0xbfb8aa3b, v120
	v_mul_f32_e32 v227, 0xbfb8aa3b, v121
	v_mul_f32_e32 v228, 0xbfb8aa3b, v114
	v_mul_f32_e32 v229, 0xbfb8aa3b, v115
	v_mul_f32_e32 v230, 0xbfb8aa3b, v116
	v_mul_f32_e32 v231, 0xbfb8aa3b, v117
	v_exp_f32_e32 v224, v224
	v_exp_f32_e32 v225, v225
	v_exp_f32_e32 v226, v226
	v_exp_f32_e32 v227, v227
	v_exp_f32_e32 v228, v228
	v_exp_f32_e32 v229, v229
	v_exp_f32_e32 v230, v230
	v_exp_f32_e32 v231, v231
	v_add_f32_e32 v224, 1.0, v224
	v_add_f32_e32 v225, 1.0, v225
	v_add_f32_e32 v226, 1.0, v226
	v_add_f32_e32 v227, 1.0, v227
	v_add_f32_e32 v228, 1.0, v228
	v_add_f32_e32 v229, 1.0, v229
	v_add_f32_e32 v230, 1.0, v230
	v_add_f32_e32 v231, 1.0, v231
	v_rcp_f32_e32 v224, v224
	v_rcp_f32_e32 v225, v225
	v_rcp_f32_e32 v226, v226
	v_rcp_f32_e32 v227, v227
	v_rcp_f32_e32 v228, v228
	v_rcp_f32_e32 v229, v229
	v_rcp_f32_e32 v230, v230
	v_rcp_f32_e32 v231, v231
	v_pk_mul_f32 v[224:225], v[118:119], v[224:225]
	v_pk_mul_f32 v[226:227], v[120:121], v[226:227]
	v_pk_mul_f32 v[228:229], v[114:115], v[228:229]
	v_pk_mul_f32 v[230:231], v[116:117], v[230:231]
	v_cvt_pk_bf16_f32 v204, v224, v225
	v_cvt_pk_bf16_f32 v205, v226, v227
	v_cvt_pk_bf16_f32 v206, v228, v229
	v_cvt_pk_bf16_f32 v207, v230, v231
	v_mul_f32_e32 v132, 0xbfb8aa3b, v126
	v_mul_f32_e32 v133, 0xbfb8aa3b, v127
	v_mul_f32_e32 v134, 0xbfb8aa3b, v128
	v_mul_f32_e32 v135, 0xbfb8aa3b, v129
	v_mul_f32_e32 v136, 0xbfb8aa3b, v122
	v_mul_f32_e32 v137, 0xbfb8aa3b, v123
	v_mul_f32_e32 v138, 0xbfb8aa3b, v124
	v_mul_f32_e32 v139, 0xbfb8aa3b, v125
	v_exp_f32_e32 v132, v132
	v_exp_f32_e32 v133, v133
	v_exp_f32_e32 v134, v134
	v_exp_f32_e32 v135, v135
	v_exp_f32_e32 v136, v136
	v_exp_f32_e32 v137, v137
	v_exp_f32_e32 v138, v138
	v_exp_f32_e32 v139, v139
	v_add_f32_e32 v132, 1.0, v132
	v_add_f32_e32 v133, 1.0, v133
	v_add_f32_e32 v134, 1.0, v134
	v_add_f32_e32 v135, 1.0, v135
	v_add_f32_e32 v136, 1.0, v136
	v_add_f32_e32 v137, 1.0, v137
	v_add_f32_e32 v138, 1.0, v138
	v_add_f32_e32 v139, 1.0, v139
	v_rcp_f32_e32 v132, v132
	v_rcp_f32_e32 v133, v133
	v_rcp_f32_e32 v134, v134
	v_rcp_f32_e32 v135, v135
	v_rcp_f32_e32 v136, v136
	v_rcp_f32_e32 v137, v137
	v_rcp_f32_e32 v138, v138
	v_rcp_f32_e32 v139, v139
	v_pk_mul_f32 v[132:133], v[126:127], v[132:133]
	v_pk_mul_f32 v[134:135], v[128:129], v[134:135]
	v_pk_mul_f32 v[136:137], v[122:123], v[136:137]
	v_pk_mul_f32 v[138:139], v[124:125], v[138:139]
	v_cvt_pk_bf16_f32 v200, v132, v133
	v_cvt_pk_bf16_f32 v201, v134, v135
	v_cvt_pk_bf16_f32 v202, v136, v137
	v_cvt_pk_bf16_f32 v203, v138, v139
	v_cndmask_b32_dpp v208, v204, v200, vcc quad_perm:[1,0,3,2] row_mask:0xf bank_mask:0xf
	v_cndmask_b32_dpp v209, v205, v201, vcc quad_perm:[1,0,3,2] row_mask:0xf bank_mask:0xf
	v_cndmask_b32_dpp v210, v206, v202, vcc quad_perm:[1,0,3,2] row_mask:0xf bank_mask:0xf
	v_cndmask_b32_dpp v211, v207, v203, vcc quad_perm:[1,0,3,2] row_mask:0xf bank_mask:0xf
	s_not_b64 vcc, vcc
	v_cndmask_b32_dpp v212, v200, v204, vcc quad_perm:[1,0,3,2] row_mask:0xf bank_mask:0xf
	v_cndmask_b32_dpp v213, v201, v205, vcc quad_perm:[1,0,3,2] row_mask:0xf bank_mask:0xf
	v_cndmask_b32_dpp v214, v202, v206, vcc quad_perm:[1,0,3,2] row_mask:0xf bank_mask:0xf
	v_cndmask_b32_dpp v215, v203, v207, vcc quad_perm:[1,0,3,2] row_mask:0xf bank_mask:0xf
	s_not_b64 vcc, vcc
	global_store_dwordx4 v[130:131], v[208:211], off
	global_store_dwordx4 v[130:131], v[212:215], off offset:1024
	v_lshl_add_u64 v[130:131], v[130:131], 0, s[4:5]
	v_mul_f32_e32 v224, 0xbfb8aa3b, v102
	v_mul_f32_e32 v225, 0xbfb8aa3b, v103
	v_mul_f32_e32 v226, 0xbfb8aa3b, v104
	v_mul_f32_e32 v227, 0xbfb8aa3b, v105
	v_mul_f32_e32 v228, 0xbfb8aa3b, v98
	v_mul_f32_e32 v229, 0xbfb8aa3b, v99
	v_mul_f32_e32 v230, 0xbfb8aa3b, v100
	v_mul_f32_e32 v231, 0xbfb8aa3b, v101
	v_exp_f32_e32 v224, v224
	v_exp_f32_e32 v225, v225
	v_exp_f32_e32 v226, v226
	v_exp_f32_e32 v227, v227
	v_exp_f32_e32 v228, v228
	v_exp_f32_e32 v229, v229
	v_exp_f32_e32 v230, v230
	v_exp_f32_e32 v231, v231
	v_add_f32_e32 v224, 1.0, v224
	v_add_f32_e32 v225, 1.0, v225
	v_add_f32_e32 v226, 1.0, v226
	v_add_f32_e32 v227, 1.0, v227
	v_add_f32_e32 v228, 1.0, v228
	v_add_f32_e32 v229, 1.0, v229
	v_add_f32_e32 v230, 1.0, v230
	v_add_f32_e32 v231, 1.0, v231
	v_rcp_f32_e32 v224, v224
	v_rcp_f32_e32 v225, v225
	v_rcp_f32_e32 v226, v226
	v_rcp_f32_e32 v227, v227
	v_rcp_f32_e32 v228, v228
	v_rcp_f32_e32 v229, v229
	v_rcp_f32_e32 v230, v230
	v_rcp_f32_e32 v231, v231
	v_pk_mul_f32 v[224:225], v[102:103], v[224:225]
	v_pk_mul_f32 v[226:227], v[104:105], v[226:227]
	v_pk_mul_f32 v[228:229], v[98:99], v[228:229]
	v_pk_mul_f32 v[230:231], v[100:101], v[230:231]
	v_cvt_pk_bf16_f32 v204, v224, v225
	v_cvt_pk_bf16_f32 v205, v226, v227
	v_cvt_pk_bf16_f32 v206, v228, v229
	v_cvt_pk_bf16_f32 v207, v230, v231
	v_mul_f32_e32 v132, 0xbfb8aa3b, v110
	v_mul_f32_e32 v133, 0xbfb8aa3b, v111
	v_mul_f32_e32 v134, 0xbfb8aa3b, v112
	v_mul_f32_e32 v135, 0xbfb8aa3b, v113
; __device__ __forceinline__ unsigned cvt_pk_bf16(float lo, float hi) { unsigned r; asm volatile("v_cvt_pk_bf16_f32 %0, %1, %2" : "=v"(r) : "v"(lo), "v"(hi)); return r; }
; __device__ __forceinline__ float silu_f(float x) { return x * __builtin_amdgcn_rcpf(1.f + __expf(-x)); }
;     __device__ __forceinline__ void operator()(const f32x4 (&acc)[2][2][4][2], const pg8::Unit& u, int wr, int wc, int fr, int fq) const {
;     ...
;         } else {
;             const bool act = (sec == 3 || sec == 7);
;             const int col0 = 256 * half + 64 * wc + 8 * fq;
; #pragma unroll
;             for (int ai = 0; ai < 2; ++ai)
; #pragma unroll
;                 for (int m = 0; m < 4; ++m) {
;                     bf16_t* rowp = base + (size_t)(row0 + ai * 128 + m * 16) * 512 + col0;
; #pragma unroll
;                     for (int bj = 0; bj < 2; ++bj) { f32x4 v0 = acc[ai][bj][m][0], v1 = acc[ai][bj][m][1];
;                         if (act) { v0 = (f32x4){silu_f(v0[0]), silu_f(v0[1]), silu_f(v0[2]), silu_f(v0[3])}; v1 = (f32x4){silu_f(v1[0]), silu_f(v1[1]), silu_f(v1[2]), silu_f(v1[3])}; }
;                         u32x4 w; w.x = cvt_pk_bf16(v0[0], v0[1]); w.y = cvt_pk_bf16(v0[2], v0[3]); w.z = cvt_pk_bf16(v1[0], v1[1]); w.w = cvt_pk_bf16(v1[2], v1[3]);
;                         *(u32x4*)(rowp + 32 * bj) = w; }
;                 }
	v_mul_f32_e32 v136, 0xbfb8aa3b, v106
	v_mul_f32_e32 v137, 0xbfb8aa3b, v107
	v_mul_f32_e32 v138, 0xbfb8aa3b, v108
	v_mul_f32_e32 v139, 0xbfb8aa3b, v109
	v_exp_f32_e32 v132, v132
	v_exp_f32_e32 v133, v133
	v_exp_f32_e32 v134, v134
	v_exp_f32_e32 v135, v135
	v_exp_f32_e32 v136, v136
	v_exp_f32_e32 v137, v137
	v_exp_f32_e32 v138, v138
	v_exp_f32_e32 v139, v139
	v_add_f32_e32 v132, 1.0, v132
	v_add_f32_e32 v133, 1.0, v133
	v_add_f32_e32 v134, 1.0, v134
	v_add_f32_e32 v135, 1.0, v135
	v_add_f32_e32 v136, 1.0, v136
	v_add_f32_e32 v137, 1.0, v137
	v_add_f32_e32 v138, 1.0, v138
	v_add_f32_e32 v139, 1.0, v139
	v_rcp_f32_e32 v132, v132
	v_rcp_f32_e32 v133, v133
	v_rcp_f32_e32 v134, v134
	v_rcp_f32_e32 v135, v135
	v_rcp_f32_e32 v136, v136
	v_rcp_f32_e32 v137, v137
	v_rcp_f32_e32 v138, v138
	v_rcp_f32_e32 v139, v139
	v_pk_mul_f32 v[132:133], v[110:111], v[132:133]
	v_pk_mul_f32 v[134:135], v[112:113], v[134:135]
	v_pk_mul_f32 v[136:137], v[106:107], v[136:137]
	v_pk_mul_f32 v[138:139], v[108:109], v[138:139]
	v_cvt_pk_bf16_f32 v200, v132, v133
	v_cvt_pk_bf16_f32 v201, v134, v135
	v_cvt_pk_bf16_f32 v202, v136, v137
	v_cvt_pk_bf16_f32 v203, v138, v139
	v_cndmask_b32_dpp v216, v204, v200, vcc quad_perm:[1,0,3,2] row_mask:0xf bank_mask:0xf
	v_cndmask_b32_dpp v217, v205, v201, vcc quad_perm:[1,0,3,2] row_mask:0xf bank_mask:0xf
	v_cndmask_b32_dpp v218, v206, v202, vcc quad_perm:[1,0,3,2] row_mask:0xf bank_mask:0xf
	v_cndmask_b32_dpp v219, v207, v203, vcc quad_perm:[1,0,3,2] row_mask:0xf bank_mask:0xf
	s_not_b64 vcc, vcc
	v_cndmask_b32_dpp v220, v200, v204, vcc quad_perm:[1,0,3,2] row_mask:0xf bank_mask:0xf
	v_cndmask_b32_dpp v221, v201, v205, vcc quad_perm:[1,0,3,2] row_mask:0xf bank_mask:0xf
	v_cndmask_b32_dpp v222, v202, v206, vcc quad_perm:[1,0,3,2] row_mask:0xf bank_mask:0xf
	v_cndmask_b32_dpp v223, v203, v207, vcc quad_perm:[1,0,3,2] row_mask:0xf bank_mask:0xf
	s_not_b64 vcc, vcc
	global_store_dwordx4 v[130:131], v[216:219], off
	global_store_dwordx4 v[130:131], v[220:223], off offset:1024
	v_lshl_add_u64 v[130:131], v[130:131], 0, s[4:5]
	v_mul_f32_e32 v224, 0xbfb8aa3b, v86
	v_mul_f32_e32 v225, 0xbfb8aa3b, v87
	v_mul_f32_e32 v226, 0xbfb8aa3b, v88
	v_mul_f32_e32 v227, 0xbfb8aa3b, v89
	v_mul_f32_e32 v228, 0xbfb8aa3b, v82
	v_mul_f32_e32 v229, 0xbfb8aa3b, v83
	v_mul_f32_e32 v230, 0xbfb8aa3b, v84
	v_mul_f32_e32 v231, 0xbfb8aa3b, v85
	v_exp_f32_e32 v224, v224
	v_exp_f32_e32 v225, v225
	v_exp_f32_e32 v226, v226
	v_exp_f32_e32 v227, v227
	v_exp_f32_e32 v228, v228
	v_exp_f32_e32 v229, v229
	v_exp_f32_e32 v230, v230
	v_exp_f32_e32 v231, v231
	v_add_f32_e32 v224, 1.0, v224
	v_add_f32_e32 v225, 1.0, v225
	v_add_f32_e32 v226, 1.0, v226
	v_add_f32_e32 v227, 1.0, v227
	v_add_f32_e32 v228, 1.0, v228
	v_add_f32_e32 v229, 1.0, v229
	v_add_f32_e32 v230, 1.0, v230
	v_add_f32_e32 v231, 1.0, v231
	v_rcp_f32_e32 v224, v224
	v_rcp_f32_e32 v225, v225
	v_rcp_f32_e32 v226, v226
	v_rcp_f32_e32 v227, v227
	v_rcp_f32_e32 v228, v228
	v_rcp_f32_e32 v229, v229
	v_rcp_f32_e32 v230, v230
	v_rcp_f32_e32 v231, v231
	v_pk_mul_f32 v[224:225], v[86:87], v[224:225]
	v_pk_mul_f32 v[226:227], v[88:89], v[226:227]
	v_pk_mul_f32 v[228:229], v[82:83], v[228:229]
	v_pk_mul_f32 v[230:231], v[84:85], v[230:231]
	v_cvt_pk_bf16_f32 v204, v224, v225
	v_cvt_pk_bf16_f32 v205, v226, v227
	v_cvt_pk_bf16_f32 v206, v228, v229
	v_cvt_pk_bf16_f32 v207, v230, v231
	v_mul_f32_e32 v132, 0xbfb8aa3b, v94
	v_mul_f32_e32 v133, 0xbfb8aa3b, v95
	v_mul_f32_e32 v134, 0xbfb8aa3b, v96
	v_mul_f32_e32 v135, 0xbfb8aa3b, v97
	v_mul_f32_e32 v136, 0xbfb8aa3b, v90
	v_mul_f32_e32 v137, 0xbfb8aa3b, v91
	v_mul_f32_e32 v138, 0xbfb8aa3b, v92
	v_mul_f32_e32 v139, 0xbfb8aa3b, v93
	v_exp_f32_e32 v132, v132
	v_exp_f32_e32 v133, v133
	v_exp_f32_e32 v134, v134
	v_exp_f32_e32 v135, v135
	v_exp_f32_e32 v136, v136
	v_exp_f32_e32 v137, v137
	v_exp_f32_e32 v138, v138
	v_exp_f32_e32 v139, v139
	v_add_f32_e32 v132, 1.0, v132
	v_add_f32_e32 v133, 1.0, v133
	v_add_f32_e32 v134, 1.0, v134
	v_add_f32_e32 v135, 1.0, v135
	v_add_f32_e32 v136, 1.0, v136
	v_add_f32_e32 v137, 1.0, v137
	v_add_f32_e32 v138, 1.0, v138
	v_add_f32_e32 v139, 1.0, v139
	v_rcp_f32_e32 v132, v132
	v_rcp_f32_e32 v133, v133
	v_rcp_f32_e32 v134, v134
	v_rcp_f32_e32 v135, v135
	v_rcp_f32_e32 v136, v136
	v_rcp_f32_e32 v137, v137
	v_rcp_f32_e32 v138, v138
	v_rcp_f32_e32 v139, v139
	v_pk_mul_f32 v[132:133], v[94:95], v[132:133]
	v_pk_mul_f32 v[134:135], v[96:97], v[134:135]
	v_pk_mul_f32 v[136:137], v[90:91], v[136:137]
	v_pk_mul_f32 v[138:139], v[92:93], v[138:139]
	v_cvt_pk_bf16_f32 v200, v132, v133
	v_cvt_pk_bf16_f32 v201, v134, v135
	v_cvt_pk_bf16_f32 v202, v136, v137
	v_cvt_pk_bf16_f32 v203, v138, v139
	v_cndmask_b32_dpp v208, v204, v200, vcc quad_perm:[1,0,3,2] row_mask:0xf bank_mask:0xf
	v_cndmask_b32_dpp v209, v205, v201, vcc quad_perm:[1,0,3,2] row_mask:0xf bank_mask:0xf
	v_cndmask_b32_dpp v210, v206, v202, vcc quad_perm:[1,0,3,2] row_mask:0xf bank_mask:0xf
	v_cndmask_b32_dpp v211, v207, v203, vcc quad_perm:[1,0,3,2] row_mask:0xf bank_mask:0xf
	s_not_b64 vcc, vcc
	v_cndmask_b32_dpp v212, v200, v204, vcc quad_perm:[1,0,3,2] row_mask:0xf bank_mask:0xf
	v_cndmask_b32_dpp v213, v201, v205, vcc quad_perm:[1,0,3,2] row_mask:0xf bank_mask:0xf
	v_cndmask_b32_dpp v214, v202, v206, vcc quad_perm:[1,0,3,2] row_mask:0xf bank_mask:0xf
	v_cndmask_b32_dpp v215, v203, v207, vcc quad_perm:[1,0,3,2] row_mask:0xf bank_mask:0xf
	s_not_b64 vcc, vcc
	global_store_dwordx4 v[130:131], v[208:211], off
	global_store_dwordx4 v[130:131], v[212:215], off offset:1024
	v_lshl_add_u64 v[130:131], v[130:131], 0, s[4:5]
	v_mul_f32_e32 v224, 0xbfb8aa3b, v70
	v_mul_f32_e32 v225, 0xbfb8aa3b, v71
; __device__ __forceinline__ unsigned cvt_pk_bf16(float lo, float hi) { unsigned r; asm volatile("v_cvt_pk_bf16_f32 %0, %1, %2" : "=v"(r) : "v"(lo), "v"(hi)); return r; }
; __device__ __forceinline__ float silu_f(float x) { return x * __builtin_amdgcn_rcpf(1.f + __expf(-x)); }
;     __device__ __forceinline__ void operator()(const f32x4 (&acc)[2][2][4][2], const pg8::Unit& u, int wr, int wc, int fr, int fq) const {
;     ...
;         } else {
;             const bool act = (sec == 3 || sec == 7);
;             const int col0 = 256 * half + 64 * wc + 8 * fq;
; #pragma unroll
;             for (int ai = 0; ai < 2; ++ai)
; #pragma unroll
;                 for (int m = 0; m < 4; ++m) {
;                     bf16_t* rowp = base + (size_t)(row0 + ai * 128 + m * 16) * 512 + col0;
; #pragma unroll
;                     for (int bj = 0; bj < 2; ++bj) { f32x4 v0 = acc[ai][bj][m][0], v1 = acc[ai][bj][m][1];
;                         if (act) { v0 = (f32x4){silu_f(v0[0]), silu_f(v0[1]), silu_f(v0[2]), silu_f(v0[3])}; v1 = (f32x4){silu_f(v1[0]), silu_f(v1[1]), silu_f(v1[2]), silu_f(v1[3])}; }
;                         u32x4 w; w.x = cvt_pk_bf16(v0[0], v0[1]); w.y = cvt_pk_bf16(v0[2], v0[3]); w.z = cvt_pk_bf16(v1[0], v1[1]); w.w = cvt_pk_bf16(v1[2], v1[3]);
;                         *(u32x4*)(rowp + 32 * bj) = w; }
;                 }
	v_mul_f32_e32 v226, 0xbfb8aa3b, v72
	v_mul_f32_e32 v227, 0xbfb8aa3b, v73
	v_mul_f32_e32 v228, 0xbfb8aa3b, v66
	v_mul_f32_e32 v229, 0xbfb8aa3b, v67
	v_mul_f32_e32 v230, 0xbfb8aa3b, v68
	v_mul_f32_e32 v231, 0xbfb8aa3b, v69
	v_exp_f32_e32 v224, v224
	v_exp_f32_e32 v225, v225
	v_exp_f32_e32 v226, v226
	v_exp_f32_e32 v227, v227
	v_exp_f32_e32 v228, v228
	v_exp_f32_e32 v229, v229
	v_exp_f32_e32 v230, v230
	v_exp_f32_e32 v231, v231
	v_add_f32_e32 v224, 1.0, v224
	v_add_f32_e32 v225, 1.0, v225
	v_add_f32_e32 v226, 1.0, v226
	v_add_f32_e32 v227, 1.0, v227
	v_add_f32_e32 v228, 1.0, v228
	v_add_f32_e32 v229, 1.0, v229
	v_add_f32_e32 v230, 1.0, v230
	v_add_f32_e32 v231, 1.0, v231
	v_rcp_f32_e32 v224, v224
	v_rcp_f32_e32 v225, v225
	v_rcp_f32_e32 v226, v226
	v_rcp_f32_e32 v227, v227
	v_rcp_f32_e32 v228, v228
	v_rcp_f32_e32 v229, v229
	v_rcp_f32_e32 v230, v230
	v_rcp_f32_e32 v231, v231
	v_pk_mul_f32 v[224:225], v[70:71], v[224:225]
	v_pk_mul_f32 v[226:227], v[72:73], v[226:227]
	v_pk_mul_f32 v[228:229], v[66:67], v[228:229]
	v_pk_mul_f32 v[230:231], v[68:69], v[230:231]
	v_cvt_pk_bf16_f32 v204, v224, v225
	v_cvt_pk_bf16_f32 v205, v226, v227
	v_cvt_pk_bf16_f32 v206, v228, v229
	v_cvt_pk_bf16_f32 v207, v230, v231
	v_mul_f32_e32 v132, 0xbfb8aa3b, v78
	v_mul_f32_e32 v133, 0xbfb8aa3b, v79
	v_mul_f32_e32 v134, 0xbfb8aa3b, v80
	v_mul_f32_e32 v135, 0xbfb8aa3b, v81
	v_mul_f32_e32 v136, 0xbfb8aa3b, v74
	v_mul_f32_e32 v137, 0xbfb8aa3b, v75
	v_mul_f32_e32 v138, 0xbfb8aa3b, v76
	v_mul_f32_e32 v139, 0xbfb8aa3b, v77
	v_exp_f32_e32 v132, v132
	v_exp_f32_e32 v133, v133
	v_exp_f32_e32 v134, v134
	v_exp_f32_e32 v135, v135
	v_exp_f32_e32 v136, v136
	v_exp_f32_e32 v137, v137
	v_exp_f32_e32 v138, v138
	v_exp_f32_e32 v139, v139
	v_add_f32_e32 v132, 1.0, v132
	v_add_f32_e32 v133, 1.0, v133
	v_add_f32_e32 v134, 1.0, v134
	v_add_f32_e32 v135, 1.0, v135
	v_add_f32_e32 v136, 1.0, v136
	v_add_f32_e32 v137, 1.0, v137
	v_add_f32_e32 v138, 1.0, v138
	v_add_f32_e32 v139, 1.0, v139
	v_rcp_f32_e32 v132, v132
	v_rcp_f32_e32 v133, v133
	v_rcp_f32_e32 v134, v134
	v_rcp_f32_e32 v135, v135
	v_rcp_f32_e32 v136, v136
	v_rcp_f32_e32 v137, v137
	v_rcp_f32_e32 v138, v138
	v_rcp_f32_e32 v139, v139
	v_pk_mul_f32 v[132:133], v[78:79], v[132:133]
	v_pk_mul_f32 v[134:135], v[80:81], v[134:135]
	v_pk_mul_f32 v[136:137], v[74:75], v[136:137]
	v_pk_mul_f32 v[138:139], v[76:77], v[138:139]
	v_cvt_pk_bf16_f32 v200, v132, v133
	v_cvt_pk_bf16_f32 v201, v134, v135
	v_cvt_pk_bf16_f32 v202, v136, v137
	v_cvt_pk_bf16_f32 v203, v138, v139
	v_cndmask_b32_dpp v216, v204, v200, vcc quad_perm:[1,0,3,2] row_mask:0xf bank_mask:0xf
	v_cndmask_b32_dpp v217, v205, v201, vcc quad_perm:[1,0,3,2] row_mask:0xf bank_mask:0xf
	v_cndmask_b32_dpp v218, v206, v202, vcc quad_perm:[1,0,3,2] row_mask:0xf bank_mask:0xf
	v_cndmask_b32_dpp v219, v207, v203, vcc quad_perm:[1,0,3,2] row_mask:0xf bank_mask:0xf
	s_not_b64 vcc, vcc
	v_cndmask_b32_dpp v220, v200, v204, vcc quad_perm:[1,0,3,2] row_mask:0xf bank_mask:0xf
	v_cndmask_b32_dpp v221, v201, v205, vcc quad_perm:[1,0,3,2] row_mask:0xf bank_mask:0xf
	v_cndmask_b32_dpp v222, v202, v206, vcc quad_perm:[1,0,3,2] row_mask:0xf bank_mask:0xf
	v_cndmask_b32_dpp v223, v203, v207, vcc quad_perm:[1,0,3,2] row_mask:0xf bank_mask:0xf
	s_not_b64 vcc, vcc
	global_store_dwordx4 v[130:131], v[216:219], off
	global_store_dwordx4 v[130:131], v[220:223], off offset:1024
	s_mov_b64 s[4:5], 0x14000
	v_lshl_add_u64 v[130:131], v[130:131], 0, s[4:5]
	s_mov_b64 s[4:5], 0x4000
	v_mul_f32_e32 v224, 0xbfb8aa3b, v54
	v_mul_f32_e32 v225, 0xbfb8aa3b, v55
	v_mul_f32_e32 v226, 0xbfb8aa3b, v56
	v_mul_f32_e32 v227, 0xbfb8aa3b, v57
	v_mul_f32_e32 v228, 0xbfb8aa3b, v50
	v_mul_f32_e32 v229, 0xbfb8aa3b, v51
	v_mul_f32_e32 v230, 0xbfb8aa3b, v52
	v_mul_f32_e32 v231, 0xbfb8aa3b, v53
	v_exp_f32_e32 v224, v224
	v_exp_f32_e32 v225, v225
	v_exp_f32_e32 v226, v226
	v_exp_f32_e32 v227, v227
	v_exp_f32_e32 v228, v228
	v_exp_f32_e32 v229, v229
	v_exp_f32_e32 v230, v230
	v_exp_f32_e32 v231, v231
	v_add_f32_e32 v224, 1.0, v224
	v_add_f32_e32 v225, 1.0, v225
	v_add_f32_e32 v226, 1.0, v226
	v_add_f32_e32 v227, 1.0, v227
	v_add_f32_e32 v228, 1.0, v228
	v_add_f32_e32 v229, 1.0, v229
	v_add_f32_e32 v230, 1.0, v230
	v_add_f32_e32 v231, 1.0, v231
	v_rcp_f32_e32 v224, v224
	v_rcp_f32_e32 v225, v225
	v_rcp_f32_e32 v226, v226
	v_rcp_f32_e32 v227, v227
	v_rcp_f32_e32 v228, v228
	v_rcp_f32_e32 v229, v229
	v_rcp_f32_e32 v230, v230
	v_rcp_f32_e32 v231, v231
	v_pk_mul_f32 v[224:225], v[54:55], v[224:225]
	v_pk_mul_f32 v[226:227], v[56:57], v[226:227]
	v_pk_mul_f32 v[228:229], v[50:51], v[228:229]
	v_pk_mul_f32 v[230:231], v[52:53], v[230:231]
	v_cvt_pk_bf16_f32 v204, v224, v225
	v_cvt_pk_bf16_f32 v205, v226, v227
	v_cvt_pk_bf16_f32 v206, v228, v229
	v_cvt_pk_bf16_f32 v207, v230, v231
	v_mul_f32_e32 v132, 0xbfb8aa3b, v62
	v_mul_f32_e32 v133, 0xbfb8aa3b, v63
	v_mul_f32_e32 v134, 0xbfb8aa3b, v64
	v_mul_f32_e32 v135, 0xbfb8aa3b, v65
	v_mul_f32_e32 v136, 0xbfb8aa3b, v58
	v_mul_f32_e32 v137, 0xbfb8aa3b, v59
	v_mul_f32_e32 v138, 0xbfb8aa3b, v60
	v_mul_f32_e32 v139, 0xbfb8aa3b, v61
	v_exp_f32_e32 v132, v132
	v_exp_f32_e32 v133, v133
	v_exp_f32_e32 v134, v134
	v_exp_f32_e32 v135, v135
	v_exp_f32_e32 v136, v136
	v_exp_f32_e32 v137, v137
	v_exp_f32_e32 v138, v138
	v_exp_f32_e32 v139, v139
	v_add_f32_e32 v132, 1.0, v132
	v_add_f32_e32 v133, 1.0, v133
	v_add_f32_e32 v134, 1.0, v134
	v_add_f32_e32 v135, 1.0, v135
	v_add_f32_e32 v136, 1.0, v136
	v_add_f32_e32 v137, 1.0, v137
	v_add_f32_e32 v138, 1.0, v138
	v_add_f32_e32 v139, 1.0, v139
	v_rcp_f32_e32 v132, v132
	v_rcp_f32_e32 v133, v133
	v_rcp_f32_e32 v134, v134
	v_rcp_f32_e32 v135, v135
	v_rcp_f32_e32 v136, v136
; __device__ __forceinline__ unsigned cvt_pk_bf16(float lo, float hi) { unsigned r; asm volatile("v_cvt_pk_bf16_f32 %0, %1, %2" : "=v"(r) : "v"(lo), "v"(hi)); return r; }
; __device__ __forceinline__ float silu_f(float x) { return x * __builtin_amdgcn_rcpf(1.f + __expf(-x)); }
;     __device__ __forceinline__ void operator()(const f32x4 (&acc)[2][2][4][2], const pg8::Unit& u, int wr, int wc, int fr, int fq) const {
;     ...
;         } else {
;             const bool act = (sec == 3 || sec == 7);
;             const int col0 = 256 * half + 64 * wc + 8 * fq;
; #pragma unroll
;             for (int ai = 0; ai < 2; ++ai)
; #pragma unroll
;                 for (int m = 0; m < 4; ++m) {
;                     bf16_t* rowp = base + (size_t)(row0 + ai * 128 + m * 16) * 512 + col0;
; #pragma unroll
;                     for (int bj = 0; bj < 2; ++bj) { f32x4 v0 = acc[ai][bj][m][0], v1 = acc[ai][bj][m][1];
;                         if (act) { v0 = (f32x4){silu_f(v0[0]), silu_f(v0[1]), silu_f(v0[2]), silu_f(v0[3])}; v1 = (f32x4){silu_f(v1[0]), silu_f(v1[1]), silu_f(v1[2]), silu_f(v1[3])}; }
;                         u32x4 w; w.x = cvt_pk_bf16(v0[0], v0[1]); w.y = cvt_pk_bf16(v0[2], v0[3]); w.z = cvt_pk_bf16(v1[0], v1[1]); w.w = cvt_pk_bf16(v1[2], v1[3]);
;                         *(u32x4*)(rowp + 32 * bj) = w; }
;                 }
	v_rcp_f32_e32 v137, v137
	v_rcp_f32_e32 v138, v138
	v_rcp_f32_e32 v139, v139
	v_pk_mul_f32 v[132:133], v[62:63], v[132:133]
	v_pk_mul_f32 v[134:135], v[64:65], v[134:135]
	v_pk_mul_f32 v[136:137], v[58:59], v[136:137]
	v_pk_mul_f32 v[138:139], v[60:61], v[138:139]
	v_cvt_pk_bf16_f32 v200, v132, v133
	v_cvt_pk_bf16_f32 v201, v134, v135
	v_cvt_pk_bf16_f32 v202, v136, v137
	v_cvt_pk_bf16_f32 v203, v138, v139
	v_cndmask_b32_dpp v208, v204, v200, vcc quad_perm:[1,0,3,2] row_mask:0xf bank_mask:0xf
	v_cndmask_b32_dpp v209, v205, v201, vcc quad_perm:[1,0,3,2] row_mask:0xf bank_mask:0xf
	v_cndmask_b32_dpp v210, v206, v202, vcc quad_perm:[1,0,3,2] row_mask:0xf bank_mask:0xf
	v_cndmask_b32_dpp v211, v207, v203, vcc quad_perm:[1,0,3,2] row_mask:0xf bank_mask:0xf
	s_not_b64 vcc, vcc
	v_cndmask_b32_dpp v212, v200, v204, vcc quad_perm:[1,0,3,2] row_mask:0xf bank_mask:0xf
	v_cndmask_b32_dpp v213, v201, v205, vcc quad_perm:[1,0,3,2] row_mask:0xf bank_mask:0xf
	v_cndmask_b32_dpp v214, v202, v206, vcc quad_perm:[1,0,3,2] row_mask:0xf bank_mask:0xf
	v_cndmask_b32_dpp v215, v203, v207, vcc quad_perm:[1,0,3,2] row_mask:0xf bank_mask:0xf
	s_not_b64 vcc, vcc
	global_store_dwordx4 v[130:131], v[208:211], off
	global_store_dwordx4 v[130:131], v[212:215], off offset:1024
	v_lshl_add_u64 v[130:131], v[130:131], 0, s[4:5]
	v_mul_f32_e32 v224, 0xbfb8aa3b, v38
	v_mul_f32_e32 v225, 0xbfb8aa3b, v39
	v_mul_f32_e32 v226, 0xbfb8aa3b, v40
	v_mul_f32_e32 v227, 0xbfb8aa3b, v41
	v_mul_f32_e32 v228, 0xbfb8aa3b, v34
	v_mul_f32_e32 v229, 0xbfb8aa3b, v35
	v_mul_f32_e32 v230, 0xbfb8aa3b, v36
	v_mul_f32_e32 v231, 0xbfb8aa3b, v37
	v_exp_f32_e32 v224, v224
	v_exp_f32_e32 v225, v225
	v_exp_f32_e32 v226, v226
	v_exp_f32_e32 v227, v227
	v_exp_f32_e32 v228, v228
	v_exp_f32_e32 v229, v229
	v_exp_f32_e32 v230, v230
	v_exp_f32_e32 v231, v231
	v_add_f32_e32 v224, 1.0, v224
	v_add_f32_e32 v225, 1.0, v225
	v_add_f32_e32 v226, 1.0, v226
	v_add_f32_e32 v227, 1.0, v227
	v_add_f32_e32 v228, 1.0, v228
	v_add_f32_e32 v229, 1.0, v229
	v_add_f32_e32 v230, 1.0, v230
	v_add_f32_e32 v231, 1.0, v231
	v_rcp_f32_e32 v224, v224
	v_rcp_f32_e32 v225, v225
	v_rcp_f32_e32 v226, v226
	v_rcp_f32_e32 v227, v227
	v_rcp_f32_e32 v228, v228
	v_rcp_f32_e32 v229, v229
	v_rcp_f32_e32 v230, v230
	v_rcp_f32_e32 v231, v231
	v_pk_mul_f32 v[224:225], v[38:39], v[224:225]
	v_pk_mul_f32 v[226:227], v[40:41], v[226:227]
	v_pk_mul_f32 v[228:229], v[34:35], v[228:229]
	v_pk_mul_f32 v[230:231], v[36:37], v[230:231]
	v_cvt_pk_bf16_f32 v204, v224, v225
	v_cvt_pk_bf16_f32 v205, v226, v227
	v_cvt_pk_bf16_f32 v206, v228, v229
	v_cvt_pk_bf16_f32 v207, v230, v231
	v_mul_f32_e32 v132, 0xbfb8aa3b, v46
	v_mul_f32_e32 v133, 0xbfb8aa3b, v47
	v_mul_f32_e32 v134, 0xbfb8aa3b, v48
	v_mul_f32_e32 v135, 0xbfb8aa3b, v49
	v_mul_f32_e32 v136, 0xbfb8aa3b, v42
	v_mul_f32_e32 v137, 0xbfb8aa3b, v43
	v_mul_f32_e32 v138, 0xbfb8aa3b, v44
	v_mul_f32_e32 v139, 0xbfb8aa3b, v45
	v_exp_f32_e32 v132, v132
	v_exp_f32_e32 v133, v133
	v_exp_f32_e32 v134, v134
	v_exp_f32_e32 v135, v135
	v_exp_f32_e32 v136, v136
	v_exp_f32_e32 v137, v137
	v_exp_f32_e32 v138, v138
	v_exp_f32_e32 v139, v139
	v_add_f32_e32 v132, 1.0, v132
	v_add_f32_e32 v133, 1.0, v133
	v_add_f32_e32 v134, 1.0, v134
	v_add_f32_e32 v135, 1.0, v135
	v_add_f32_e32 v136, 1.0, v136
	v_add_f32_e32 v137, 1.0, v137
	v_add_f32_e32 v138, 1.0, v138
	v_add_f32_e32 v139, 1.0, v139
	v_rcp_f32_e32 v132, v132
	v_rcp_f32_e32 v133, v133
	v_rcp_f32_e32 v134, v134
	v_rcp_f32_e32 v135, v135
	v_rcp_f32_e32 v136, v136
	v_rcp_f32_e32 v137, v137
	v_rcp_f32_e32 v138, v138
	v_rcp_f32_e32 v139, v139
	v_pk_mul_f32 v[132:133], v[46:47], v[132:133]
	v_pk_mul_f32 v[134:135], v[48:49], v[134:135]
	v_pk_mul_f32 v[136:137], v[42:43], v[136:137]
	v_pk_mul_f32 v[138:139], v[44:45], v[138:139]
	v_cvt_pk_bf16_f32 v200, v132, v133
	v_cvt_pk_bf16_f32 v201, v134, v135
	v_cvt_pk_bf16_f32 v202, v136, v137
	v_cvt_pk_bf16_f32 v203, v138, v139
	v_cndmask_b32_dpp v216, v204, v200, vcc quad_perm:[1,0,3,2] row_mask:0xf bank_mask:0xf
	v_cndmask_b32_dpp v217, v205, v201, vcc quad_perm:[1,0,3,2] row_mask:0xf bank_mask:0xf
	v_cndmask_b32_dpp v218, v206, v202, vcc quad_perm:[1,0,3,2] row_mask:0xf bank_mask:0xf
	v_cndmask_b32_dpp v219, v207, v203, vcc quad_perm:[1,0,3,2] row_mask:0xf bank_mask:0xf
	s_not_b64 vcc, vcc
	v_cndmask_b32_dpp v220, v200, v204, vcc quad_perm:[1,0,3,2] row_mask:0xf bank_mask:0xf
	v_cndmask_b32_dpp v221, v201, v205, vcc quad_perm:[1,0,3,2] row_mask:0xf bank_mask:0xf
	v_cndmask_b32_dpp v222, v202, v206, vcc quad_perm:[1,0,3,2] row_mask:0xf bank_mask:0xf
	v_cndmask_b32_dpp v223, v203, v207, vcc quad_perm:[1,0,3,2] row_mask:0xf bank_mask:0xf
	s_not_b64 vcc, vcc
	global_store_dwordx4 v[130:131], v[216:219], off
	global_store_dwordx4 v[130:131], v[220:223], off offset:1024
	v_lshl_add_u64 v[130:131], v[130:131], 0, s[4:5]
	v_mul_f32_e32 v224, 0xbfb8aa3b, v22
	v_mul_f32_e32 v225, 0xbfb8aa3b, v23
	v_mul_f32_e32 v226, 0xbfb8aa3b, v24
	v_mul_f32_e32 v227, 0xbfb8aa3b, v25
	v_mul_f32_e32 v228, 0xbfb8aa3b, v18
	v_mul_f32_e32 v229, 0xbfb8aa3b, v19
	v_mul_f32_e32 v230, 0xbfb8aa3b, v20
	v_mul_f32_e32 v231, 0xbfb8aa3b, v21
	v_exp_f32_e32 v224, v224
	v_exp_f32_e32 v225, v225
	v_exp_f32_e32 v226, v226
	v_exp_f32_e32 v227, v227
	v_exp_f32_e32 v228, v228
	v_exp_f32_e32 v229, v229
	v_exp_f32_e32 v230, v230
	v_exp_f32_e32 v231, v231
	v_add_f32_e32 v224, 1.0, v224
	v_add_f32_e32 v225, 1.0, v225
	v_add_f32_e32 v226, 1.0, v226
	v_add_f32_e32 v227, 1.0, v227
	v_add_f32_e32 v228, 1.0, v228
	v_add_f32_e32 v229, 1.0, v229
	v_add_f32_e32 v230, 1.0, v230
	v_add_f32_e32 v231, 1.0, v231
	v_rcp_f32_e32 v224, v224
	v_rcp_f32_e32 v225, v225
	v_rcp_f32_e32 v226, v226
; __device__ __forceinline__ unsigned cvt_pk_bf16(float lo, float hi) { unsigned r; asm volatile("v_cvt_pk_bf16_f32 %0, %1, %2" : "=v"(r) : "v"(lo), "v"(hi)); return r; }
; __device__ __forceinline__ float silu_f(float x) { return x * __builtin_amdgcn_rcpf(1.f + __expf(-x)); }
;     __device__ __forceinline__ void operator()(const f32x4 (&acc)[2][2][4][2], const pg8::Unit& u, int wr, int wc, int fr, int fq) const {
;     ...
;         } else {
;             const bool act = (sec == 3 || sec == 7);
;             const int col0 = 256 * half + 64 * wc + 8 * fq;
; #pragma unroll
;             for (int ai = 0; ai < 2; ++ai)
; #pragma unroll
;                 for (int m = 0; m < 4; ++m) {
;                     bf16_t* rowp = base + (size_t)(row0 + ai * 128 + m * 16) * 512 + col0;
; #pragma unroll
;                     for (int bj = 0; bj < 2; ++bj) { f32x4 v0 = acc[ai][bj][m][0], v1 = acc[ai][bj][m][1];
;                         if (act) { v0 = (f32x4){silu_f(v0[0]), silu_f(v0[1]), silu_f(v0[2]), silu_f(v0[3])}; v1 = (f32x4){silu_f(v1[0]), silu_f(v1[1]), silu_f(v1[2]), silu_f(v1[3])}; }
;                         u32x4 w; w.x = cvt_pk_bf16(v0[0], v0[1]); w.y = cvt_pk_bf16(v0[2], v0[3]); w.z = cvt_pk_bf16(v1[0], v1[1]); w.w = cvt_pk_bf16(v1[2], v1[3]);
;                         *(u32x4*)(rowp + 32 * bj) = w; }
;                 }
	v_rcp_f32_e32 v227, v227
	v_rcp_f32_e32 v228, v228
	v_rcp_f32_e32 v229, v229
	v_rcp_f32_e32 v230, v230
	v_rcp_f32_e32 v231, v231
	v_pk_mul_f32 v[224:225], v[22:23], v[224:225]
	v_pk_mul_f32 v[226:227], v[24:25], v[226:227]
	v_pk_mul_f32 v[228:229], v[18:19], v[228:229]
	v_pk_mul_f32 v[230:231], v[20:21], v[230:231]
	v_cvt_pk_bf16_f32 v204, v224, v225
	v_cvt_pk_bf16_f32 v205, v226, v227
	v_cvt_pk_bf16_f32 v206, v228, v229
	v_cvt_pk_bf16_f32 v207, v230, v231
	v_mul_f32_e32 v132, 0xbfb8aa3b, v30
	v_mul_f32_e32 v133, 0xbfb8aa3b, v31
	v_mul_f32_e32 v134, 0xbfb8aa3b, v32
	v_mul_f32_e32 v135, 0xbfb8aa3b, v33
	v_mul_f32_e32 v136, 0xbfb8aa3b, v26
	v_mul_f32_e32 v137, 0xbfb8aa3b, v27
	v_mul_f32_e32 v138, 0xbfb8aa3b, v28
	v_mul_f32_e32 v139, 0xbfb8aa3b, v29
	v_exp_f32_e32 v132, v132
	v_exp_f32_e32 v133, v133
	v_exp_f32_e32 v134, v134
	v_exp_f32_e32 v135, v135
	v_exp_f32_e32 v136, v136
	v_exp_f32_e32 v137, v137
	v_exp_f32_e32 v138, v138
	v_exp_f32_e32 v139, v139
	v_add_f32_e32 v132, 1.0, v132
	v_add_f32_e32 v133, 1.0, v133
	v_add_f32_e32 v134, 1.0, v134
	v_add_f32_e32 v135, 1.0, v135
	v_add_f32_e32 v136, 1.0, v136
	v_add_f32_e32 v137, 1.0, v137
	v_add_f32_e32 v138, 1.0, v138
	v_add_f32_e32 v139, 1.0, v139
	v_rcp_f32_e32 v132, v132
	v_rcp_f32_e32 v133, v133
	v_rcp_f32_e32 v134, v134
	v_rcp_f32_e32 v135, v135
	v_rcp_f32_e32 v136, v136
	v_rcp_f32_e32 v137, v137
	v_rcp_f32_e32 v138, v138
	v_rcp_f32_e32 v139, v139
	v_pk_mul_f32 v[132:133], v[30:31], v[132:133]
	v_pk_mul_f32 v[134:135], v[32:33], v[134:135]
	v_pk_mul_f32 v[136:137], v[26:27], v[136:137]
	v_pk_mul_f32 v[138:139], v[28:29], v[138:139]
	v_cvt_pk_bf16_f32 v200, v132, v133
	v_cvt_pk_bf16_f32 v201, v134, v135
	v_cvt_pk_bf16_f32 v202, v136, v137
	v_cvt_pk_bf16_f32 v203, v138, v139
	v_cndmask_b32_dpp v208, v204, v200, vcc quad_perm:[1,0,3,2] row_mask:0xf bank_mask:0xf
	v_cndmask_b32_dpp v209, v205, v201, vcc quad_perm:[1,0,3,2] row_mask:0xf bank_mask:0xf
	v_cndmask_b32_dpp v210, v206, v202, vcc quad_perm:[1,0,3,2] row_mask:0xf bank_mask:0xf
	v_cndmask_b32_dpp v211, v207, v203, vcc quad_perm:[1,0,3,2] row_mask:0xf bank_mask:0xf
	s_not_b64 vcc, vcc
	v_cndmask_b32_dpp v212, v200, v204, vcc quad_perm:[1,0,3,2] row_mask:0xf bank_mask:0xf
	v_cndmask_b32_dpp v213, v201, v205, vcc quad_perm:[1,0,3,2] row_mask:0xf bank_mask:0xf
	v_cndmask_b32_dpp v214, v202, v206, vcc quad_perm:[1,0,3,2] row_mask:0xf bank_mask:0xf
	v_cndmask_b32_dpp v215, v203, v207, vcc quad_perm:[1,0,3,2] row_mask:0xf bank_mask:0xf
	s_not_b64 vcc, vcc
	global_store_dwordx4 v[130:131], v[208:211], off
	global_store_dwordx4 v[130:131], v[212:215], off offset:1024
	v_lshl_add_u64 v[130:131], v[130:131], 0, s[4:5]
	v_mul_f32_e32 v224, 0xbfb8aa3b, v6
	v_mul_f32_e32 v225, 0xbfb8aa3b, v7
	v_mul_f32_e32 v226, 0xbfb8aa3b, v8
	v_mul_f32_e32 v227, 0xbfb8aa3b, v9
	v_mul_f32_e32 v228, 0xbfb8aa3b, v2
	v_mul_f32_e32 v229, 0xbfb8aa3b, v3
	v_mul_f32_e32 v230, 0xbfb8aa3b, v4
	v_mul_f32_e32 v231, 0xbfb8aa3b, v5
	v_exp_f32_e32 v224, v224
	v_exp_f32_e32 v225, v225
	v_exp_f32_e32 v226, v226
	v_exp_f32_e32 v227, v227
	v_exp_f32_e32 v228, v228
	v_exp_f32_e32 v229, v229
	v_exp_f32_e32 v230, v230
	v_exp_f32_e32 v231, v231
	v_add_f32_e32 v224, 1.0, v224
	v_add_f32_e32 v225, 1.0, v225
	v_add_f32_e32 v226, 1.0, v226
	v_add_f32_e32 v227, 1.0, v227
	v_add_f32_e32 v228, 1.0, v228
	v_add_f32_e32 v229, 1.0, v229
	v_add_f32_e32 v230, 1.0, v230
	v_add_f32_e32 v231, 1.0, v231
	v_rcp_f32_e32 v224, v224
	v_rcp_f32_e32 v225, v225
	v_rcp_f32_e32 v226, v226
	v_rcp_f32_e32 v227, v227
	v_rcp_f32_e32 v228, v228
	v_rcp_f32_e32 v229, v229
	v_rcp_f32_e32 v230, v230
	v_rcp_f32_e32 v231, v231
	v_pk_mul_f32 v[224:225], v[6:7], v[224:225]
	v_pk_mul_f32 v[226:227], v[8:9], v[226:227]
	v_pk_mul_f32 v[228:229], v[2:3], v[228:229]
	v_pk_mul_f32 v[230:231], v[4:5], v[230:231]
	v_cvt_pk_bf16_f32 v204, v224, v225
	v_cvt_pk_bf16_f32 v205, v226, v227
	v_cvt_pk_bf16_f32 v206, v228, v229
	v_cvt_pk_bf16_f32 v207, v230, v231
	v_mul_f32_e32 v132, 0xbfb8aa3b, v14
	v_mul_f32_e32 v133, 0xbfb8aa3b, v15
	v_mul_f32_e32 v134, 0xbfb8aa3b, v16
	v_mul_f32_e32 v135, 0xbfb8aa3b, v17
	v_mul_f32_e32 v136, 0xbfb8aa3b, v10
	v_mul_f32_e32 v137, 0xbfb8aa3b, v11
	v_mul_f32_e32 v138, 0xbfb8aa3b, v12
	v_mul_f32_e32 v139, 0xbfb8aa3b, v13
	v_exp_f32_e32 v132, v132
	v_exp_f32_e32 v133, v133
	v_exp_f32_e32 v134, v134
	v_exp_f32_e32 v135, v135
	v_exp_f32_e32 v136, v136
	v_exp_f32_e32 v137, v137
	v_exp_f32_e32 v138, v138
	v_exp_f32_e32 v139, v139
	v_add_f32_e32 v132, 1.0, v132
	v_add_f32_e32 v133, 1.0, v133
	v_add_f32_e32 v134, 1.0, v134
	v_add_f32_e32 v135, 1.0, v135
	v_add_f32_e32 v136, 1.0, v136
	v_add_f32_e32 v137, 1.0, v137
	v_add_f32_e32 v138, 1.0, v138
	v_add_f32_e32 v139, 1.0, v139
	v_rcp_f32_e32 v132, v132
	v_rcp_f32_e32 v133, v133
	v_rcp_f32_e32 v134, v134
	v_rcp_f32_e32 v135, v135
	v_rcp_f32_e32 v136, v136
	v_rcp_f32_e32 v137, v137
	v_rcp_f32_e32 v138, v138
	v_rcp_f32_e32 v139, v139
	v_pk_mul_f32 v[132:133], v[14:15], v[132:133]
	v_pk_mul_f32 v[134:135], v[16:17], v[134:135]
	v_pk_mul_f32 v[136:137], v[10:11], v[136:137]
	v_pk_mul_f32 v[138:139], v[12:13], v[138:139]
	v_cvt_pk_bf16_f32 v200, v132, v133
	v_cvt_pk_bf16_f32 v201, v134, v135
	v_cvt_pk_bf16_f32 v202, v136, v137
	v_cvt_pk_bf16_f32 v203, v138, v139
	v_cndmask_b32_dpp v216, v204, v200, vcc quad_perm:[1,0,3,2] row_mask:0xf bank_mask:0xf
	v_cndmask_b32_dpp v217, v205, v201, vcc quad_perm:[1,0,3,2] row_mask:0xf bank_mask:0xf
	v_cndmask_b32_dpp v218, v206, v202, vcc quad_perm:[1,0,3,2] row_mask:0xf bank_mask:0xf
	v_cndmask_b32_dpp v219, v207, v203, vcc quad_perm:[1,0,3,2] row_mask:0xf bank_mask:0xf
	s_not_b64 vcc, vcc
	v_cndmask_b32_dpp v220, v200, v204, vcc quad_perm:[1,0,3,2] row_mask:0xf bank_mask:0xf
	v_cndmask_b32_dpp v221, v201, v205, vcc quad_perm:[1,0,3,2] row_mask:0xf bank_mask:0xf
	v_cndmask_b32_dpp v222, v202, v206, vcc quad_perm:[1,0,3,2] row_mask:0xf bank_mask:0xf
	v_cndmask_b32_dpp v223, v203, v207, vcc quad_perm:[1,0,3,2] row_mask:0xf bank_mask:0xf
	s_not_b64 vcc, vcc
	global_store_dwordx4 v[130:131], v[216:219], off
	global_store_dwordx4 v[130:131], v[220:223], off offset:1024
	s_branch .Lp1e_done
; __device__ __forceinline__ unsigned cvt_pk_bf16(float lo, float hi) { unsigned r; asm volatile("v_cvt_pk_bf16_f32 %0, %1, %2" : "=v"(r) : "v"(lo), "v"(hi)); return r; }
; __device__ __forceinline__ float silu_f(float x) { return x * __builtin_amdgcn_rcpf(1.f + __expf(-x)); }
;     __device__ __forceinline__ void operator()(const f32x4 (&acc)[2][2][4][2], const pg8::Unit& u, int wr, int wc, int fr, int fq) const {
;     ...
;         } else {
;             const bool act = (sec == 3 || sec == 7);
;             const int col0 = 256 * half + 64 * wc + 8 * fq;
; #pragma unroll
;             for (int ai = 0; ai < 2; ++ai)
; #pragma unroll
;                 for (int m = 0; m < 4; ++m) {
;                     bf16_t* rowp = base + (size_t)(row0 + ai * 128 + m * 16) * 512 + col0;
; #pragma unroll
;                     for (int bj = 0; bj < 2; ++bj) { f32x4 v0 = acc[ai][bj][m][0], v1 = acc[ai][bj][m][1];
;                         if (act) { v0 = (f32x4){silu_f(v0[0]), silu_f(v0[1]), silu_f(v0[2]), silu_f(v0[3])}; v1 = (f32x4){silu_f(v1[0]), silu_f(v1[1]), silu_f(v1[2]), silu_f(v1[3])}; }
;                         u32x4 w; w.x = cvt_pk_bf16(v0[0], v0[1]); w.y = cvt_pk_bf16(v0[2], v0[3]); w.z = cvt_pk_bf16(v1[0], v1[1]); w.w = cvt_pk_bf16(v1[2], v1[3]);
;                         *(u32x4*)(rowp + 32 * bj) = w; }
;                 }
.Lp1e_plain:
	v_cvt_pk_bf16_f32 v204, v118, v119
	v_cvt_pk_bf16_f32 v205, v120, v121
	v_cvt_pk_bf16_f32 v206, v114, v115
	v_cvt_pk_bf16_f32 v207, v116, v117
	v_cvt_pk_bf16_f32 v200, v126, v127
	v_cvt_pk_bf16_f32 v201, v128, v129
	v_cvt_pk_bf16_f32 v202, v122, v123
	v_cvt_pk_bf16_f32 v203, v124, v125
	v_cndmask_b32_dpp v208, v204, v200, vcc quad_perm:[1,0,3,2] row_mask:0xf bank_mask:0xf
	v_cndmask_b32_dpp v209, v205, v201, vcc quad_perm:[1,0,3,2] row_mask:0xf bank_mask:0xf
	v_cndmask_b32_dpp v210, v206, v202, vcc quad_perm:[1,0,3,2] row_mask:0xf bank_mask:0xf
	v_cndmask_b32_dpp v211, v207, v203, vcc quad_perm:[1,0,3,2] row_mask:0xf bank_mask:0xf
	s_not_b64 vcc, vcc
	v_cndmask_b32_dpp v212, v200, v204, vcc quad_perm:[1,0,3,2] row_mask:0xf bank_mask:0xf
	v_cndmask_b32_dpp v213, v201, v205, vcc quad_perm:[1,0,3,2] row_mask:0xf bank_mask:0xf
	v_cndmask_b32_dpp v214, v202, v206, vcc quad_perm:[1,0,3,2] row_mask:0xf bank_mask:0xf
	v_cndmask_b32_dpp v215, v203, v207, vcc quad_perm:[1,0,3,2] row_mask:0xf bank_mask:0xf
	s_not_b64 vcc, vcc
	global_store_dwordx4 v[130:131], v[208:211], off
	global_store_dwordx4 v[130:131], v[212:215], off offset:1024
	v_lshl_add_u64 v[130:131], v[130:131], 0, s[4:5]
	v_cvt_pk_bf16_f32 v204, v102, v103
	v_cvt_pk_bf16_f32 v205, v104, v105
	v_cvt_pk_bf16_f32 v206, v98, v99
	v_cvt_pk_bf16_f32 v207, v100, v101
	v_cvt_pk_bf16_f32 v200, v110, v111
	v_cvt_pk_bf16_f32 v201, v112, v113
	v_cvt_pk_bf16_f32 v202, v106, v107
	v_cvt_pk_bf16_f32 v203, v108, v109
	v_cndmask_b32_dpp v216, v204, v200, vcc quad_perm:[1,0,3,2] row_mask:0xf bank_mask:0xf
	v_cndmask_b32_dpp v217, v205, v201, vcc quad_perm:[1,0,3,2] row_mask:0xf bank_mask:0xf
	v_cndmask_b32_dpp v218, v206, v202, vcc quad_perm:[1,0,3,2] row_mask:0xf bank_mask:0xf
	v_cndmask_b32_dpp v219, v207, v203, vcc quad_perm:[1,0,3,2] row_mask:0xf bank_mask:0xf
	s_not_b64 vcc, vcc
	v_cndmask_b32_dpp v220, v200, v204, vcc quad_perm:[1,0,3,2] row_mask:0xf bank_mask:0xf
	v_cndmask_b32_dpp v221, v201, v205, vcc quad_perm:[1,0,3,2] row_mask:0xf bank_mask:0xf
	v_cndmask_b32_dpp v222, v202, v206, vcc quad_perm:[1,0,3,2] row_mask:0xf bank_mask:0xf
	v_cndmask_b32_dpp v223, v203, v207, vcc quad_perm:[1,0,3,2] row_mask:0xf bank_mask:0xf
	s_not_b64 vcc, vcc
	global_store_dwordx4 v[130:131], v[216:219], off
	global_store_dwordx4 v[130:131], v[220:223], off offset:1024
	v_lshl_add_u64 v[130:131], v[130:131], 0, s[4:5]
	v_cvt_pk_bf16_f32 v204, v86, v87
	v_cvt_pk_bf16_f32 v205, v88, v89
	v_cvt_pk_bf16_f32 v206, v82, v83
	v_cvt_pk_bf16_f32 v207, v84, v85
	v_cvt_pk_bf16_f32 v200, v94, v95
	v_cvt_pk_bf16_f32 v201, v96, v97
	v_cvt_pk_bf16_f32 v202, v90, v91
	v_cvt_pk_bf16_f32 v203, v92, v93
	v_cndmask_b32_dpp v208, v204, v200, vcc quad_perm:[1,0,3,2] row_mask:0xf bank_mask:0xf
	v_cndmask_b32_dpp v209, v205, v201, vcc quad_perm:[1,0,3,2] row_mask:0xf bank_mask:0xf
	v_cndmask_b32_dpp v210, v206, v202, vcc quad_perm:[1,0,3,2] row_mask:0xf bank_mask:0xf
	v_cndmask_b32_dpp v211, v207, v203, vcc quad_perm:[1,0,3,2] row_mask:0xf bank_mask:0xf
	s_not_b64 vcc, vcc
	v_cndmask_b32_dpp v212, v200, v204, vcc quad_perm:[1,0,3,2] row_mask:0xf bank_mask:0xf
	v_cndmask_b32_dpp v213, v201, v205, vcc quad_perm:[1,0,3,2] row_mask:0xf bank_mask:0xf
	v_cndmask_b32_dpp v214, v202, v206, vcc quad_perm:[1,0,3,2] row_mask:0xf bank_mask:0xf
	v_cndmask_b32_dpp v215, v203, v207, vcc quad_perm:[1,0,3,2] row_mask:0xf bank_mask:0xf
	s_not_b64 vcc, vcc
	global_store_dwordx4 v[130:131], v[208:211], off
	global_store_dwordx4 v[130:131], v[212:215], off offset:1024
	v_lshl_add_u64 v[130:131], v[130:131], 0, s[4:5]
	v_cvt_pk_bf16_f32 v204, v70, v71
	v_cvt_pk_bf16_f32 v205, v72, v73
	v_cvt_pk_bf16_f32 v206, v66, v67
	v_cvt_pk_bf16_f32 v207, v68, v69
	v_cvt_pk_bf16_f32 v200, v78, v79
	v_cvt_pk_bf16_f32 v201, v80, v81
	v_cvt_pk_bf16_f32 v202, v74, v75
	v_cvt_pk_bf16_f32 v203, v76, v77
	v_cndmask_b32_dpp v216, v204, v200, vcc quad_perm:[1,0,3,2] row_mask:0xf bank_mask:0xf
	v_cndmask_b32_dpp v217, v205, v201, vcc quad_perm:[1,0,3,2] row_mask:0xf bank_mask:0xf
	v_cndmask_b32_dpp v218, v206, v202, vcc quad_perm:[1,0,3,2] row_mask:0xf bank_mask:0xf
	v_cndmask_b32_dpp v219, v207, v203, vcc quad_perm:[1,0,3,2] row_mask:0xf bank_mask:0xf
	s_not_b64 vcc, vcc
	v_cndmask_b32_dpp v220, v200, v204, vcc quad_perm:[1,0,3,2] row_mask:0xf bank_mask:0xf
	v_cndmask_b32_dpp v221, v201, v205, vcc quad_perm:[1,0,3,2] row_mask:0xf bank_mask:0xf
	v_cndmask_b32_dpp v222, v202, v206, vcc quad_perm:[1,0,3,2] row_mask:0xf bank_mask:0xf
	v_cndmask_b32_dpp v223, v203, v207, vcc quad_perm:[1,0,3,2] row_mask:0xf bank_mask:0xf
	s_not_b64 vcc, vcc
	global_store_dwordx4 v[130:131], v[216:219], off
	global_store_dwordx4 v[130:131], v[220:223], off offset:1024
	s_mov_b64 s[4:5], 0x14000
	v_lshl_add_u64 v[130:131], v[130:131], 0, s[4:5]
	s_mov_b64 s[4:5], 0x4000
	v_cvt_pk_bf16_f32 v204, v54, v55
	v_cvt_pk_bf16_f32 v205, v56, v57
	v_cvt_pk_bf16_f32 v206, v50, v51
	v_cvt_pk_bf16_f32 v207, v52, v53
	v_cvt_pk_bf16_f32 v200, v62, v63
	v_cvt_pk_bf16_f32 v201, v64, v65
	v_cvt_pk_bf16_f32 v202, v58, v59
	v_cvt_pk_bf16_f32 v203, v60, v61
	v_cndmask_b32_dpp v208, v204, v200, vcc quad_perm:[1,0,3,2] row_mask:0xf bank_mask:0xf
	v_cndmask_b32_dpp v209, v205, v201, vcc quad_perm:[1,0,3,2] row_mask:0xf bank_mask:0xf
	v_cndmask_b32_dpp v210, v206, v202, vcc quad_perm:[1,0,3,2] row_mask:0xf bank_mask:0xf
	v_cndmask_b32_dpp v211, v207, v203, vcc quad_perm:[1,0,3,2] row_mask:0xf bank_mask:0xf
	s_not_b64 vcc, vcc
	v_cndmask_b32_dpp v212, v200, v204, vcc quad_perm:[1,0,3,2] row_mask:0xf bank_mask:0xf
	v_cndmask_b32_dpp v213, v201, v205, vcc quad_perm:[1,0,3,2] row_mask:0xf bank_mask:0xf
; __device__ __forceinline__ unsigned cvt_pk_bf16(float lo, float hi) { unsigned r; asm volatile("v_cvt_pk_bf16_f32 %0, %1, %2" : "=v"(r) : "v"(lo), "v"(hi)); return r; }
; __device__ __forceinline__ float silu_f(float x) { return x * __builtin_amdgcn_rcpf(1.f + __expf(-x)); }
;     __device__ __forceinline__ void operator()(const f32x4 (&acc)[2][2][4][2], const pg8::Unit& u, int wr, int wc, int fr, int fq) const {
;     ...
;         } else if (sec == 4 || sec == 5) {
;             const float osc = sec == 5 ? 0.08838834764831845f : 1.f;
;             const int col0 = 256 * half + 128 * (wc >> 1) + 32 * (wc & 1) + 8 * fq, i0 = 32 * (wc & 1) + 8 * fq;
;             const int tb = row0 < NP ? (row0 & 4095) : row0 - NP;
;             f32x4 c[2], sn[2], c16[2], s16[2];
; #pragma unroll
;             for (int e = 0; e < 2; ++e) { c[e] = *(const f32x4*)(ropec + tb * 64 + i0 + 4 * e); sn[e] = *(const f32x4*)(ropes + tb * 64 + i0 + 4 * e);
;                 c16[e] = *(const f32x4*)(ropec + 16 * 64 + i0 + 4 * e); s16[e] = *(const f32x4*)(ropes + 16 * 64 + i0 + 4 * e); }
;     ...
;         } else {
;             const bool act = (sec == 3 || sec == 7);
;             const int col0 = 256 * half + 64 * wc + 8 * fq;
; #pragma unroll
;             for (int ai = 0; ai < 2; ++ai)
; #pragma unroll
;                 for (int m = 0; m < 4; ++m) {
;                     bf16_t* rowp = base + (size_t)(row0 + ai * 128 + m * 16) * 512 + col0;
; #pragma unroll
;                     for (int bj = 0; bj < 2; ++bj) { f32x4 v0 = acc[ai][bj][m][0], v1 = acc[ai][bj][m][1];
;                         if (act) { v0 = (f32x4){silu_f(v0[0]), silu_f(v0[1]), silu_f(v0[2]), silu_f(v0[3])}; v1 = (f32x4){silu_f(v1[0]), silu_f(v1[1]), silu_f(v1[2]), silu_f(v1[3])}; }
;                         u32x4 w; w.x = cvt_pk_bf16(v0[0], v0[1]); w.y = cvt_pk_bf16(v0[2], v0[3]); w.z = cvt_pk_bf16(v1[0], v1[1]); w.w = cvt_pk_bf16(v1[2], v1[3]);
;                         *(u32x4*)(rowp + 32 * bj) = w; }
;                 }
	v_cndmask_b32_dpp v214, v202, v206, vcc quad_perm:[1,0,3,2] row_mask:0xf bank_mask:0xf
	v_cndmask_b32_dpp v215, v203, v207, vcc quad_perm:[1,0,3,2] row_mask:0xf bank_mask:0xf
	s_not_b64 vcc, vcc
	global_store_dwordx4 v[130:131], v[208:211], off
	global_store_dwordx4 v[130:131], v[212:215], off offset:1024
	v_lshl_add_u64 v[130:131], v[130:131], 0, s[4:5]
	v_cvt_pk_bf16_f32 v204, v38, v39
	v_cvt_pk_bf16_f32 v205, v40, v41
	v_cvt_pk_bf16_f32 v206, v34, v35
	v_cvt_pk_bf16_f32 v207, v36, v37
	v_cvt_pk_bf16_f32 v200, v46, v47
	v_cvt_pk_bf16_f32 v201, v48, v49
	v_cvt_pk_bf16_f32 v202, v42, v43
	v_cvt_pk_bf16_f32 v203, v44, v45
	v_cndmask_b32_dpp v216, v204, v200, vcc quad_perm:[1,0,3,2] row_mask:0xf bank_mask:0xf
	v_cndmask_b32_dpp v217, v205, v201, vcc quad_perm:[1,0,3,2] row_mask:0xf bank_mask:0xf
	v_cndmask_b32_dpp v218, v206, v202, vcc quad_perm:[1,0,3,2] row_mask:0xf bank_mask:0xf
	v_cndmask_b32_dpp v219, v207, v203, vcc quad_perm:[1,0,3,2] row_mask:0xf bank_mask:0xf
	s_not_b64 vcc, vcc
	v_cndmask_b32_dpp v220, v200, v204, vcc quad_perm:[1,0,3,2] row_mask:0xf bank_mask:0xf
	v_cndmask_b32_dpp v221, v201, v205, vcc quad_perm:[1,0,3,2] row_mask:0xf bank_mask:0xf
	v_cndmask_b32_dpp v222, v202, v206, vcc quad_perm:[1,0,3,2] row_mask:0xf bank_mask:0xf
	v_cndmask_b32_dpp v223, v203, v207, vcc quad_perm:[1,0,3,2] row_mask:0xf bank_mask:0xf
	s_not_b64 vcc, vcc
	global_store_dwordx4 v[130:131], v[216:219], off
	global_store_dwordx4 v[130:131], v[220:223], off offset:1024
	v_lshl_add_u64 v[130:131], v[130:131], 0, s[4:5]
	v_cvt_pk_bf16_f32 v204, v22, v23
	v_cvt_pk_bf16_f32 v205, v24, v25
	v_cvt_pk_bf16_f32 v206, v18, v19
	v_cvt_pk_bf16_f32 v207, v20, v21
	v_cvt_pk_bf16_f32 v200, v30, v31
	v_cvt_pk_bf16_f32 v201, v32, v33
	v_cvt_pk_bf16_f32 v202, v26, v27
	v_cvt_pk_bf16_f32 v203, v28, v29
	v_cndmask_b32_dpp v208, v204, v200, vcc quad_perm:[1,0,3,2] row_mask:0xf bank_mask:0xf
	v_cndmask_b32_dpp v209, v205, v201, vcc quad_perm:[1,0,3,2] row_mask:0xf bank_mask:0xf
	v_cndmask_b32_dpp v210, v206, v202, vcc quad_perm:[1,0,3,2] row_mask:0xf bank_mask:0xf
	v_cndmask_b32_dpp v211, v207, v203, vcc quad_perm:[1,0,3,2] row_mask:0xf bank_mask:0xf
	s_not_b64 vcc, vcc
	v_cndmask_b32_dpp v212, v200, v204, vcc quad_perm:[1,0,3,2] row_mask:0xf bank_mask:0xf
	v_cndmask_b32_dpp v213, v201, v205, vcc quad_perm:[1,0,3,2] row_mask:0xf bank_mask:0xf
	v_cndmask_b32_dpp v214, v202, v206, vcc quad_perm:[1,0,3,2] row_mask:0xf bank_mask:0xf
	v_cndmask_b32_dpp v215, v203, v207, vcc quad_perm:[1,0,3,2] row_mask:0xf bank_mask:0xf
	s_not_b64 vcc, vcc
	global_store_dwordx4 v[130:131], v[208:211], off
	global_store_dwordx4 v[130:131], v[212:215], off offset:1024
	v_lshl_add_u64 v[130:131], v[130:131], 0, s[4:5]
	v_cvt_pk_bf16_f32 v204, v6, v7
	v_cvt_pk_bf16_f32 v205, v8, v9
	v_cvt_pk_bf16_f32 v206, v2, v3
	v_cvt_pk_bf16_f32 v207, v4, v5
	v_cvt_pk_bf16_f32 v200, v14, v15
	v_cvt_pk_bf16_f32 v201, v16, v17
	v_cvt_pk_bf16_f32 v202, v10, v11
	v_cvt_pk_bf16_f32 v203, v12, v13
	v_cndmask_b32_dpp v216, v204, v200, vcc quad_perm:[1,0,3,2] row_mask:0xf bank_mask:0xf
	v_cndmask_b32_dpp v217, v205, v201, vcc quad_perm:[1,0,3,2] row_mask:0xf bank_mask:0xf
	v_cndmask_b32_dpp v218, v206, v202, vcc quad_perm:[1,0,3,2] row_mask:0xf bank_mask:0xf
	v_cndmask_b32_dpp v219, v207, v203, vcc quad_perm:[1,0,3,2] row_mask:0xf bank_mask:0xf
	s_not_b64 vcc, vcc
	v_cndmask_b32_dpp v220, v200, v204, vcc quad_perm:[1,0,3,2] row_mask:0xf bank_mask:0xf
	v_cndmask_b32_dpp v221, v201, v205, vcc quad_perm:[1,0,3,2] row_mask:0xf bank_mask:0xf
	v_cndmask_b32_dpp v222, v202, v206, vcc quad_perm:[1,0,3,2] row_mask:0xf bank_mask:0xf
	v_cndmask_b32_dpp v223, v203, v207, vcc quad_perm:[1,0,3,2] row_mask:0xf bank_mask:0xf
	s_not_b64 vcc, vcc
	global_store_dwordx4 v[130:131], v[216:219], off
	global_store_dwordx4 v[130:131], v[220:223], off offset:1024
.Lp1e_done:
	s_mov_b64 s[4:5], 0
.LBB0_202:
	s_and_b64 vcc, exec, s[4:5]
	s_cbranch_vccz .LBB0_204
	v_and_b32_e32 v130, 0xfcf, v172
	v_add_u32_e32 v131, 0xffff0000, v172
	v_cmp_gt_i32_e32 vcc, s77, v172
	s_cmp_eq_u32 s41, 5
	v_lshl_or_b32 v154, s27, 9, v186
	v_cndmask_b32_e32 v130, v131, v130, vcc
	v_lshlrev_b32_e32 v130, 6, v130
	v_ashrrev_i32_e32 v131, 31, v130
	v_lshlrev_b64 v[130:131], 2, v[130:131]
	v_lshl_add_u64 v[132:133], v[156:157], 0, v[130:131]
	global_load_dwordx4 v[192:195], v[132:133], off
	global_load_dwordx4 v[196:199], v[132:133], off offset:16
	v_lshl_add_u64 v[130:131], v[158:159], 0, v[130:131]
	global_load_dwordx4 v[200:203], v[130:131], off
	global_load_dwordx4 v[204:207], v[130:131], off offset:16
	global_load_dwordx4 v[142:145], v[162:163], off
	global_load_dwordx4 v[134:137], v[162:163], off offset:16
	global_load_dwordx4 v[138:141], v[160:161], off
	s_nop 0
	global_load_dwordx4 v[130:133], v[160:161], off offset:16
	s_cselect_b64 vcc, -1, 0
	v_cndmask_b32_e32 v176, 1.0, v189, vcc
	v_ashrrev_i32_e32 v173, 31, v172
	v_lshl_add_u64 v[178:179], s[48:49], 0, v[154:155]
	v_lshlrev_b64 v[174:175], 10, v[172:173]
	v_lshl_add_u64 v[174:175], v[178:179], 0, v[174:175]
	v_or_b32_e32 v208, 16, v172
	v_ashrrev_i32_e32 v209, 31, v208
	s_waitcnt vmcnt(0)
; __device__ __forceinline__ unsigned cvt_pk_bf16(float lo, float hi) { unsigned r; asm volatile("v_cvt_pk_bf16_f32 %0, %1, %2" : "=v"(r) : "v"(lo), "v"(hi)); return r; }
;     __device__ __forceinline__ void operator()(const f32x4 (&acc)[2][2][4][2], const pg8::Unit& u, int wr, int wc, int fr, int fq) const {
;     ...
;             for (int k = 0; k < 12; ++k) {
;                 if (k < 4 || k >= 8) {
;                     const int ai = k >> 3, m = k & 3;
;                     const int row = row0 + ai * 128 + m * 16;
;                     const f32x4 c0 = c[0] * osc, c1 = c[1] * osc, s0 = sn[0] * osc, s1 = sn[1] * osc;
;                     const f32x4 a0 = acc[ai][0][m][0], a1 = acc[ai][0][m][1], b0 = acc[ai][1][m][0], b1 = acc[ai][1][m][1];
;                     const f32x4 o10 = a0 * c0 - b0 * s0, o11 = a1 * c1 - b1 * s1, o20 = a0 * s0 + b0 * c0, o21 = a1 * s1 + b1 * c1;
;                     bf16_t* rowp = base + (size_t)row * 512 + col0;
;                     u32x4 w; w.x = cvt_pk_bf16(o10[0], o10[1]); w.y = cvt_pk_bf16(o10[2], o10[3]); w.z = cvt_pk_bf16(o11[0], o11[1]); w.w = cvt_pk_bf16(o11[2], o11[3]);
;                     *(u32x4*)(rowp) = w;
;                     w.x = cvt_pk_bf16(o20[0], o20[1]); w.y = cvt_pk_bf16(o20[2], o20[3]); w.z = cvt_pk_bf16(o21[0], o21[1]); w.w = cvt_pk_bf16(o21[2], o21[3]);
;                     *(u32x4*)(rowp + 64) = w;
;                 }
;                 if (k < 11) {
; #pragma unroll
;                     for (int e = 0; e < 2; ++e) { const f32x4 cn = c[e] * c16[e] - sn[e] * s16[e]; sn[e] = sn[e] * c16[e] + c[e] * s16[e]; c[e] = cn; } }
;             }
	v_pk_mul_f32 v[220:221], v[176:177], v[200:201] op_sel_hi:[0,1]
	v_pk_mul_f32 v[218:219], v[176:177], v[202:203] op_sel_hi:[0,1]
	v_pk_mul_f32 v[212:213], v[176:177], v[192:193] op_sel_hi:[0,1]
	v_pk_mul_f32 v[228:229], v[200:201], v[142:143]
	v_pk_mul_f32 v[244:245], v[118:119], v[220:221]
	v_pk_mul_f32 v[210:211], v[176:177], v[194:195] op_sel_hi:[0,1]
	v_pk_mul_f32 v[222:223], v[176:177], v[206:207] op_sel_hi:[0,1]
	v_pk_mul_f32 v[224:225], v[176:177], v[204:205] op_sel_hi:[0,1]
	v_pk_mul_f32 v[226:227], v[202:203], v[144:145]
	v_pk_mul_f32 v[230:231], v[194:195], v[144:145]
	v_pk_mul_f32 v[232:233], v[192:193], v[142:143]
	v_pk_mul_f32 v[242:243], v[120:121], v[218:219]
	v_pk_fma_f32 v[228:229], v[192:193], v[138:139], v[228:229] neg_lo:[0,0,1] neg_hi:[0,0,1]
	v_pk_fma_f32 v[192:193], v[126:127], v[212:213], v[244:245] neg_lo:[0,0,1] neg_hi:[0,0,1]
	v_pk_mul_f32 v[214:215], v[176:177], v[198:199] op_sel_hi:[0,1]
	v_pk_mul_f32 v[216:217], v[176:177], v[196:197] op_sel_hi:[0,1]
	v_pk_mul_f32 v[234:235], v[206:207], v[136:137]
	v_pk_mul_f32 v[238:239], v[198:199], v[136:137]
	v_pk_mul_f32 v[240:241], v[196:197], v[134:135]
	v_pk_mul_f32 v[246:247], v[116:117], v[222:223]
	v_pk_mul_f32 v[248:249], v[114:115], v[224:225]
	v_pk_mul_f32 v[218:219], v[128:129], v[218:219]
	v_pk_mul_f32 v[220:221], v[126:127], v[220:221]
	v_pk_fma_f32 v[226:227], v[194:195], v[140:141], v[226:227] neg_lo:[0,0,1] neg_hi:[0,0,1]
	v_pk_fma_f32 v[202:203], v[202:203], v[140:141], v[230:231]
	v_pk_fma_f32 v[194:195], v[128:129], v[210:211], v[242:243] neg_lo:[0,0,1] neg_hi:[0,0,1]
	v_cvt_pk_bf16_f32 v192, v192, v193
	v_pk_mul_f32 v[236:237], v[204:205], v[134:135]
	v_cvt_pk_bf16_f32 v193, v194, v195
	v_pk_mul_f32 v[222:223], v[124:125], v[222:223]
	v_pk_mul_f32 v[224:225], v[122:123], v[224:225]
	v_pk_fma_f32 v[200:201], v[200:201], v[138:139], v[232:233]
	v_pk_fma_f32 v[198:199], v[198:199], v[132:133], v[234:235] neg_lo:[0,0,1] neg_hi:[0,0,1]
	v_pk_fma_f32 v[206:207], v[206:207], v[132:133], v[238:239]
	v_pk_fma_f32 v[204:205], v[204:205], v[130:131], v[240:241]
	v_pk_fma_f32 v[230:231], v[124:125], v[214:215], v[246:247] neg_lo:[0,0,1] neg_hi:[0,0,1]
	v_pk_fma_f32 v[232:233], v[122:123], v[216:217], v[248:249] neg_lo:[0,0,1] neg_hi:[0,0,1]
	v_pk_fma_f32 v[210:211], v[120:121], v[210:211], v[218:219]
	v_pk_fma_f32 v[212:213], v[118:119], v[212:213], v[220:221]
	v_pk_mul_f32 v[218:219], v[176:177], v[226:227] op_sel_hi:[0,1]
	v_pk_mul_f32 v[234:235], v[176:177], v[202:203] op_sel_hi:[0,1]
	v_cvt_pk_bf16_f32 v194, v232, v233
	v_cvt_pk_bf16_f32 v195, v230, v231
	global_store_dwordx4 v[174:175], v[192:195], off
	v_pk_fma_f32 v[196:197], v[196:197], v[130:131], v[236:237] neg_lo:[0,0,1] neg_hi:[0,0,1]
	v_pk_fma_f32 v[214:215], v[116:117], v[214:215], v[222:223]
	v_cvt_pk_bf16_f32 v192, v212, v213
	v_cvt_pk_bf16_f32 v193, v210, v211
	v_pk_fma_f32 v[216:217], v[114:115], v[216:217], v[224:225]
	v_pk_mul_f32 v[222:223], v[176:177], v[198:199] op_sel_hi:[0,1]
	v_pk_mul_f32 v[238:239], v[176:177], v[206:207] op_sel_hi:[0,1]
	v_pk_mul_f32 v[240:241], v[176:177], v[204:205] op_sel_hi:[0,1]
	v_pk_mul_f32 v[230:231], v[104:105], v[234:235]
	v_cvt_pk_bf16_f32 v194, v216, v217
	v_cvt_pk_bf16_f32 v195, v214, v215
	global_store_dwordx4 v[174:175], v[192:195], off offset:128
	v_pk_mul_f32 v[224:225], v[176:177], v[196:197] op_sel_hi:[0,1]
	v_pk_mul_f32 v[236:237], v[176:177], v[200:201] op_sel_hi:[0,1]
	v_pk_mul_f32 v[192:193], v[104:105], v[218:219]
	v_pk_mul_f32 v[242:243], v[100:101], v[238:239]
	v_pk_mul_f32 v[244:245], v[98:99], v[240:241]
	v_pk_fma_f32 v[210:211], v[112:113], v[218:219], v[230:231] neg_lo:[0,0,1] neg_hi:[0,0,1]
	v_pk_fma_f32 v[218:219], v[112:113], v[234:235], v[192:193]
	v_pk_mul_f32 v[192:193], v[100:101], v[222:223]
	v_pk_mul_f32 v[220:221], v[176:177], v[228:229] op_sel_hi:[0,1]
	v_pk_mul_f32 v[232:233], v[102:103], v[236:237]
	v_pk_fma_f32 v[214:215], v[108:109], v[222:223], v[242:243] neg_lo:[0,0,1] neg_hi:[0,0,1]
	v_pk_fma_f32 v[194:195], v[106:107], v[224:225], v[244:245] neg_lo:[0,0,1] neg_hi:[0,0,1]
	v_pk_fma_f32 v[222:223], v[108:109], v[238:239], v[192:193]
	v_lshlrev_b64 v[192:193], 10, v[208:209]
	v_pk_fma_f32 v[212:213], v[110:111], v[220:221], v[232:233] neg_lo:[0,0,1] neg_hi:[0,0,1]
	v_pk_mul_f32 v[216:217], v[102:103], v[220:221]
	v_pk_mul_f32 v[220:221], v[98:99], v[224:225]
	v_lshl_add_u64 v[208:209], v[178:179], 0, v[192:193]
	v_cvt_pk_bf16_f32 v192, v212, v213
	v_cvt_pk_bf16_f32 v193, v210, v211
	v_cvt_pk_bf16_f32 v194, v194, v195
	v_cvt_pk_bf16_f32 v195, v214, v215
	v_pk_fma_f32 v[216:217], v[110:111], v[236:237], v[216:217]
	v_pk_fma_f32 v[220:221], v[106:107], v[240:241], v[220:221]
	global_store_dwordx4 v[208:209], v[192:195], off
	s_nop 1
	v_cvt_pk_bf16_f32 v192, v216, v217
	v_cvt_pk_bf16_f32 v193, v218, v219
	v_cvt_pk_bf16_f32 v194, v220, v221
	v_cvt_pk_bf16_f32 v195, v222, v223
	global_store_dwordx4 v[208:209], v[192:195], off offset:128
	s_nop 1
	v_pk_mul_f32 v[192:193], v[144:145], v[202:203]
	v_pk_mul_f32 v[194:195], v[142:143], v[200:201]
	v_pk_fma_f32 v[208:209], v[140:141], v[226:227], v[192:193] neg_lo:[0,0,1] neg_hi:[0,0,1]
	v_pk_fma_f32 v[210:211], v[138:139], v[228:229], v[194:195] neg_lo:[0,0,1] neg_hi:[0,0,1]
	v_pk_mul_f32 v[192:193], v[144:145], v[226:227]
	v_pk_mul_f32 v[194:195], v[142:143], v[228:229]
	v_pk_fma_f32 v[202:203], v[140:141], v[202:203], v[192:193]
	v_pk_fma_f32 v[200:201], v[138:139], v[200:201], v[194:195]
	v_pk_mul_f32 v[192:193], v[136:137], v[206:207]
	v_pk_mul_f32 v[194:195], v[134:135], v[204:205]
	v_pk_fma_f32 v[212:213], v[132:133], v[198:199], v[192:193] neg_lo:[0,0,1] neg_hi:[0,0,1]
; __device__ __forceinline__ unsigned cvt_pk_bf16(float lo, float hi) { unsigned r; asm volatile("v_cvt_pk_bf16_f32 %0, %1, %2" : "=v"(r) : "v"(lo), "v"(hi)); return r; }
;     __device__ __forceinline__ void operator()(const f32x4 (&acc)[2][2][4][2], const pg8::Unit& u, int wr, int wc, int fr, int fq) const {
;     ...
;             for (int k = 0; k < 12; ++k) {
;                 if (k < 4 || k >= 8) {
;                     const int ai = k >> 3, m = k & 3;
;                     const int row = row0 + ai * 128 + m * 16;
;                     const f32x4 c0 = c[0] * osc, c1 = c[1] * osc, s0 = sn[0] * osc, s1 = sn[1] * osc;
;                     const f32x4 a0 = acc[ai][0][m][0], a1 = acc[ai][0][m][1], b0 = acc[ai][1][m][0], b1 = acc[ai][1][m][1];
;                     const f32x4 o10 = a0 * c0 - b0 * s0, o11 = a1 * c1 - b1 * s1, o20 = a0 * s0 + b0 * c0, o21 = a1 * s1 + b1 * c1;
;                     bf16_t* rowp = base + (size_t)row * 512 + col0;
;                     u32x4 w; w.x = cvt_pk_bf16(o10[0], o10[1]); w.y = cvt_pk_bf16(o10[2], o10[3]); w.z = cvt_pk_bf16(o11[0], o11[1]); w.w = cvt_pk_bf16(o11[2], o11[3]);
;                     *(u32x4*)(rowp) = w;
;                     w.x = cvt_pk_bf16(o20[0], o20[1]); w.y = cvt_pk_bf16(o20[2], o20[3]); w.z = cvt_pk_bf16(o21[0], o21[1]); w.w = cvt_pk_bf16(o21[2], o21[3]);
;                     *(u32x4*)(rowp + 64) = w;
;                 }
;                 if (k < 11) {
; #pragma unroll
;                     for (int e = 0; e < 2; ++e) { const f32x4 cn = c[e] * c16[e] - sn[e] * s16[e]; sn[e] = sn[e] * c16[e] + c[e] * s16[e]; c[e] = cn; } }
;             }
	v_pk_fma_f32 v[214:215], v[130:131], v[196:197], v[194:195] neg_lo:[0,0,1] neg_hi:[0,0,1]
	v_pk_mul_f32 v[192:193], v[136:137], v[198:199]
	v_pk_mul_f32 v[194:195], v[134:135], v[196:197]
	v_pk_mul_f32 v[218:219], v[176:177], v[202:203] op_sel_hi:[0,1]
	v_pk_fma_f32 v[196:197], v[132:133], v[206:207], v[192:193]
	v_pk_fma_f32 v[198:199], v[130:131], v[204:205], v[194:195]
	v_or_b32_e32 v192, 32, v172
	v_pk_mul_f32 v[194:195], v[176:177], v[208:209] op_sel_hi:[0,1]
	v_pk_mul_f32 v[220:221], v[176:177], v[200:201] op_sel_hi:[0,1]
	v_pk_mul_f32 v[226:227], v[88:89], v[218:219]
	v_pk_mul_f32 v[204:205], v[176:177], v[210:211] op_sel_hi:[0,1]
	v_pk_mul_f32 v[206:207], v[176:177], v[212:213] op_sel_hi:[0,1]
	v_pk_mul_f32 v[222:223], v[176:177], v[196:197] op_sel_hi:[0,1]
	v_pk_mul_f32 v[224:225], v[176:177], v[198:199] op_sel_hi:[0,1]
	v_pk_mul_f32 v[228:229], v[86:87], v[220:221]
	v_pk_fma_f32 v[226:227], v[96:97], v[194:195], v[226:227] neg_lo:[0,0,1] neg_hi:[0,0,1]
	v_pk_mul_f32 v[194:195], v[88:89], v[194:195]
	v_ashrrev_i32_e32 v193, 31, v192
	v_pk_mul_f32 v[216:217], v[176:177], v[214:215] op_sel_hi:[0,1]
	v_pk_fma_f32 v[228:229], v[94:95], v[204:205], v[228:229] neg_lo:[0,0,1] neg_hi:[0,0,1]
	v_pk_mul_f32 v[230:231], v[84:85], v[222:223]
	v_pk_mul_f32 v[232:233], v[82:83], v[224:225]
	v_pk_mul_f32 v[204:205], v[86:87], v[204:205]
	v_pk_fma_f32 v[218:219], v[96:97], v[218:219], v[194:195]
	v_pk_mul_f32 v[194:195], v[84:85], v[206:207]
	v_lshlrev_b64 v[192:193], 10, v[192:193]
	v_pk_fma_f32 v[230:231], v[92:93], v[206:207], v[230:231] neg_lo:[0,0,1] neg_hi:[0,0,1]
	v_pk_fma_f32 v[232:233], v[90:91], v[216:217], v[232:233] neg_lo:[0,0,1] neg_hi:[0,0,1]
	v_pk_fma_f32 v[204:205], v[94:95], v[220:221], v[204:205]
	v_pk_mul_f32 v[206:207], v[82:83], v[216:217]
	v_pk_fma_f32 v[216:217], v[92:93], v[222:223], v[194:195]
	v_lshl_add_u64 v[220:221], v[178:179], 0, v[192:193]
	v_cvt_pk_bf16_f32 v192, v228, v229
	v_cvt_pk_bf16_f32 v193, v226, v227
	v_cvt_pk_bf16_f32 v194, v232, v233
	v_cvt_pk_bf16_f32 v195, v230, v231
	v_pk_fma_f32 v[206:207], v[90:91], v[224:225], v[206:207]
	global_store_dwordx4 v[220:221], v[192:195], off
	s_nop 1
	v_cvt_pk_bf16_f32 v192, v204, v205
	v_cvt_pk_bf16_f32 v193, v218, v219
	v_cvt_pk_bf16_f32 v194, v206, v207
	v_cvt_pk_bf16_f32 v195, v216, v217
	global_store_dwordx4 v[220:221], v[192:195], off offset:128
	s_nop 1
	v_pk_mul_f32 v[192:193], v[144:145], v[202:203]
	v_pk_mul_f32 v[194:195], v[142:143], v[200:201]
	v_pk_fma_f32 v[204:205], v[140:141], v[208:209], v[192:193] neg_lo:[0,0,1] neg_hi:[0,0,1]
	v_pk_fma_f32 v[206:207], v[138:139], v[210:211], v[194:195] neg_lo:[0,0,1] neg_hi:[0,0,1]
	v_pk_mul_f32 v[192:193], v[144:145], v[208:209]
	v_pk_mul_f32 v[194:195], v[142:143], v[210:211]
	v_pk_fma_f32 v[202:203], v[140:141], v[202:203], v[192:193]
	v_pk_fma_f32 v[200:201], v[138:139], v[200:201], v[194:195]
	v_pk_mul_f32 v[192:193], v[136:137], v[196:197]
	v_pk_mul_f32 v[194:195], v[134:135], v[198:199]
	v_pk_fma_f32 v[208:209], v[132:133], v[212:213], v[192:193] neg_lo:[0,0,1] neg_hi:[0,0,1]
	v_pk_fma_f32 v[210:211], v[130:131], v[214:215], v[194:195] neg_lo:[0,0,1] neg_hi:[0,0,1]
	v_pk_mul_f32 v[192:193], v[136:137], v[212:213]
	v_pk_mul_f32 v[194:195], v[134:135], v[214:215]
	v_pk_mul_f32 v[218:219], v[176:177], v[202:203] op_sel_hi:[0,1]
	v_pk_fma_f32 v[196:197], v[132:133], v[196:197], v[192:193]
	v_pk_fma_f32 v[198:199], v[130:131], v[198:199], v[194:195]
	v_or_b32_e32 v192, 48, v172
	v_pk_mul_f32 v[194:195], v[176:177], v[204:205] op_sel_hi:[0,1]
	v_pk_mul_f32 v[226:227], v[72:73], v[218:219]
	v_pk_mul_f32 v[214:215], v[176:177], v[208:209] op_sel_hi:[0,1]
	v_pk_mul_f32 v[220:221], v[176:177], v[200:201] op_sel_hi:[0,1]
	v_pk_mul_f32 v[222:223], v[176:177], v[196:197] op_sel_hi:[0,1]
	v_pk_mul_f32 v[224:225], v[176:177], v[198:199] op_sel_hi:[0,1]
	v_pk_fma_f32 v[226:227], v[80:81], v[194:195], v[226:227] neg_lo:[0,0,1] neg_hi:[0,0,1]
	v_pk_mul_f32 v[194:195], v[72:73], v[194:195]
	v_ashrrev_i32_e32 v193, 31, v192
	v_pk_mul_f32 v[212:213], v[176:177], v[206:207] op_sel_hi:[0,1]
	v_pk_mul_f32 v[216:217], v[176:177], v[210:211] op_sel_hi:[0,1]
	v_pk_mul_f32 v[228:229], v[70:71], v[220:221]
	v_pk_mul_f32 v[230:231], v[68:69], v[222:223]
	v_pk_mul_f32 v[232:233], v[66:67], v[224:225]
	v_pk_fma_f32 v[218:219], v[80:81], v[218:219], v[194:195]
	v_pk_mul_f32 v[194:195], v[68:69], v[214:215]
	v_lshlrev_b64 v[192:193], 10, v[192:193]
	v_pk_fma_f32 v[228:229], v[78:79], v[212:213], v[228:229] neg_lo:[0,0,1] neg_hi:[0,0,1]
	v_pk_fma_f32 v[230:231], v[76:77], v[214:215], v[230:231] neg_lo:[0,0,1] neg_hi:[0,0,1]
	v_pk_fma_f32 v[232:233], v[74:75], v[216:217], v[232:233] neg_lo:[0,0,1] neg_hi:[0,0,1]
	v_pk_mul_f32 v[212:213], v[70:71], v[212:213]
	v_pk_mul_f32 v[214:215], v[66:67], v[216:217]
	v_pk_fma_f32 v[216:217], v[76:77], v[222:223], v[194:195]
	v_lshl_add_u64 v[178:179], v[178:179], 0, v[192:193]
	v_cvt_pk_bf16_f32 v192, v228, v229
	v_cvt_pk_bf16_f32 v193, v226, v227
	v_cvt_pk_bf16_f32 v194, v232, v233
	v_cvt_pk_bf16_f32 v195, v230, v231
	v_pk_fma_f32 v[212:213], v[78:79], v[220:221], v[212:213]
	v_pk_fma_f32 v[214:215], v[74:75], v[224:225], v[214:215]
	global_store_dwordx4 v[178:179], v[192:195], off
	s_nop 1
	v_cvt_pk_bf16_f32 v192, v212, v213
	v_cvt_pk_bf16_f32 v193, v218, v219
	v_cvt_pk_bf16_f32 v194, v214, v215
	v_cvt_pk_bf16_f32 v195, v216, v217
	global_store_dwordx4 v[178:179], v[192:195], off offset:128
	v_pk_mul_f32 v[178:179], v[144:145], v[202:203]
	s_nop 0
	v_pk_mul_f32 v[194:195], v[144:145], v[204:205]
	v_pk_mul_f32 v[192:193], v[142:143], v[200:201]
	v_pk_fma_f32 v[178:179], v[140:141], v[204:205], v[178:179] neg_lo:[0,0,1] neg_hi:[0,0,1]
; __device__ __forceinline__ unsigned cvt_pk_bf16(float lo, float hi) { unsigned r; asm volatile("v_cvt_pk_bf16_f32 %0, %1, %2" : "=v"(r) : "v"(lo), "v"(hi)); return r; }
;     __device__ __forceinline__ void operator()(const f32x4 (&acc)[2][2][4][2], const pg8::Unit& u, int wr, int wc, int fr, int fq) const {
;     ...
;             for (int k = 0; k < 12; ++k) {
;                 if (k < 4 || k >= 8) {
;                     const int ai = k >> 3, m = k & 3;
;                     const int row = row0 + ai * 128 + m * 16;
;                     const f32x4 c0 = c[0] * osc, c1 = c[1] * osc, s0 = sn[0] * osc, s1 = sn[1] * osc;
;                     const f32x4 a0 = acc[ai][0][m][0], a1 = acc[ai][0][m][1], b0 = acc[ai][1][m][0], b1 = acc[ai][1][m][1];
;                     const f32x4 o10 = a0 * c0 - b0 * s0, o11 = a1 * c1 - b1 * s1, o20 = a0 * s0 + b0 * c0, o21 = a1 * s1 + b1 * c1;
;                     bf16_t* rowp = base + (size_t)row * 512 + col0;
;                     u32x4 w; w.x = cvt_pk_bf16(o10[0], o10[1]); w.y = cvt_pk_bf16(o10[2], o10[3]); w.z = cvt_pk_bf16(o11[0], o11[1]); w.w = cvt_pk_bf16(o11[2], o11[3]);
;                     *(u32x4*)(rowp) = w;
;                     w.x = cvt_pk_bf16(o20[0], o20[1]); w.y = cvt_pk_bf16(o20[2], o20[3]); w.z = cvt_pk_bf16(o21[0], o21[1]); w.w = cvt_pk_bf16(o21[2], o21[3]);
;                     *(u32x4*)(rowp + 64) = w;
;     ...
;                 if (k < 11) {
; #pragma unroll
;                     for (int e = 0; e < 2; ++e) { const f32x4 cn = c[e] * c16[e] - sn[e] * s16[e]; sn[e] = sn[e] * c16[e] + c[e] * s16[e]; c[e] = cn; } }
;             }
	v_pk_mul_f32 v[204:205], v[142:143], v[206:207]
	v_pk_fma_f32 v[194:195], v[140:141], v[202:203], v[194:195]
	v_pk_mul_f32 v[202:203], v[136:137], v[196:197]
	v_pk_fma_f32 v[192:193], v[138:139], v[206:207], v[192:193] neg_lo:[0,0,1] neg_hi:[0,0,1]
	v_pk_fma_f32 v[200:201], v[138:139], v[200:201], v[204:205]
	v_pk_fma_f32 v[202:203], v[132:133], v[208:209], v[202:203] neg_lo:[0,0,1] neg_hi:[0,0,1]
	v_pk_mul_f32 v[206:207], v[136:137], v[208:209]
	v_pk_mul_f32 v[208:209], v[134:135], v[210:211]
	v_pk_mul_f32 v[204:205], v[134:135], v[198:199]
	v_pk_fma_f32 v[196:197], v[132:133], v[196:197], v[206:207]
	v_pk_fma_f32 v[198:199], v[130:131], v[198:199], v[208:209]
	v_pk_mul_f32 v[206:207], v[144:145], v[194:195]
	v_pk_mul_f32 v[208:209], v[142:143], v[200:201]
	v_pk_fma_f32 v[206:207], v[140:141], v[178:179], v[206:207] neg_lo:[0,0,1] neg_hi:[0,0,1]
	v_pk_fma_f32 v[208:209], v[138:139], v[192:193], v[208:209] neg_lo:[0,0,1] neg_hi:[0,0,1]
	v_pk_mul_f32 v[178:179], v[144:145], v[178:179]
	v_pk_mul_f32 v[192:193], v[142:143], v[192:193]
	v_pk_fma_f32 v[204:205], v[130:131], v[210:211], v[204:205] neg_lo:[0,0,1] neg_hi:[0,0,1]
	v_pk_fma_f32 v[178:179], v[140:141], v[194:195], v[178:179]
	v_pk_fma_f32 v[192:193], v[138:139], v[200:201], v[192:193]
	v_pk_mul_f32 v[194:195], v[136:137], v[196:197]
	v_pk_mul_f32 v[200:201], v[134:135], v[198:199]
	v_pk_fma_f32 v[194:195], v[132:133], v[202:203], v[194:195] neg_lo:[0,0,1] neg_hi:[0,0,1]
	v_pk_fma_f32 v[200:201], v[130:131], v[204:205], v[200:201] neg_lo:[0,0,1] neg_hi:[0,0,1]
	v_pk_mul_f32 v[202:203], v[136:137], v[202:203]
	v_pk_mul_f32 v[204:205], v[134:135], v[204:205]
	v_pk_fma_f32 v[196:197], v[132:133], v[196:197], v[202:203]
	v_pk_fma_f32 v[198:199], v[130:131], v[198:199], v[204:205]
	v_pk_mul_f32 v[202:203], v[144:145], v[178:179]
	v_pk_mul_f32 v[204:205], v[142:143], v[192:193]
	v_pk_fma_f32 v[202:203], v[140:141], v[206:207], v[202:203] neg_lo:[0,0,1] neg_hi:[0,0,1]
	v_pk_fma_f32 v[204:205], v[138:139], v[208:209], v[204:205] neg_lo:[0,0,1] neg_hi:[0,0,1]
	v_pk_mul_f32 v[206:207], v[144:145], v[206:207]
	v_pk_mul_f32 v[208:209], v[142:143], v[208:209]
	v_pk_fma_f32 v[178:179], v[140:141], v[178:179], v[206:207]
	v_pk_fma_f32 v[192:193], v[138:139], v[192:193], v[208:209]
	v_pk_mul_f32 v[206:207], v[136:137], v[196:197]
	v_pk_mul_f32 v[208:209], v[134:135], v[198:199]
	v_pk_fma_f32 v[206:207], v[132:133], v[194:195], v[206:207] neg_lo:[0,0,1] neg_hi:[0,0,1]
	v_pk_fma_f32 v[208:209], v[130:131], v[200:201], v[208:209] neg_lo:[0,0,1] neg_hi:[0,0,1]
	v_pk_mul_f32 v[194:195], v[136:137], v[194:195]
	v_pk_mul_f32 v[200:201], v[134:135], v[200:201]
	v_pk_fma_f32 v[194:195], v[132:133], v[196:197], v[194:195]
	v_pk_fma_f32 v[196:197], v[130:131], v[198:199], v[200:201]
	v_pk_mul_f32 v[198:199], v[144:145], v[178:179]
	v_pk_mul_f32 v[200:201], v[142:143], v[192:193]
	v_pk_fma_f32 v[198:199], v[140:141], v[202:203], v[198:199] neg_lo:[0,0,1] neg_hi:[0,0,1]
	v_pk_fma_f32 v[200:201], v[138:139], v[204:205], v[200:201] neg_lo:[0,0,1] neg_hi:[0,0,1]
	v_pk_mul_f32 v[202:203], v[144:145], v[202:203]
	v_pk_mul_f32 v[204:205], v[142:143], v[204:205]
	v_pk_fma_f32 v[178:179], v[140:141], v[178:179], v[202:203]
	v_pk_fma_f32 v[192:193], v[138:139], v[192:193], v[204:205]
	v_pk_mul_f32 v[202:203], v[136:137], v[194:195]
	v_pk_mul_f32 v[204:205], v[134:135], v[196:197]
	v_pk_fma_f32 v[202:203], v[132:133], v[206:207], v[202:203] neg_lo:[0,0,1] neg_hi:[0,0,1]
	v_pk_fma_f32 v[204:205], v[130:131], v[208:209], v[204:205] neg_lo:[0,0,1] neg_hi:[0,0,1]
	v_pk_mul_f32 v[206:207], v[136:137], v[206:207]
	v_pk_mul_f32 v[208:209], v[134:135], v[208:209]
	v_pk_fma_f32 v[194:195], v[132:133], v[194:195], v[206:207]
	v_pk_fma_f32 v[196:197], v[130:131], v[196:197], v[208:209]
	v_pk_mul_f32 v[206:207], v[144:145], v[178:179]
	v_pk_mul_f32 v[208:209], v[142:143], v[192:193]
	v_pk_fma_f32 v[206:207], v[140:141], v[198:199], v[206:207] neg_lo:[0,0,1] neg_hi:[0,0,1]
	v_pk_fma_f32 v[208:209], v[138:139], v[200:201], v[208:209] neg_lo:[0,0,1] neg_hi:[0,0,1]
	v_pk_mul_f32 v[198:199], v[144:145], v[198:199]
	v_pk_mul_f32 v[200:201], v[142:143], v[200:201]
	v_pk_fma_f32 v[178:179], v[140:141], v[178:179], v[198:199]
	v_pk_fma_f32 v[198:199], v[138:139], v[192:193], v[200:201]
	v_pk_mul_f32 v[192:193], v[136:137], v[194:195]
	v_pk_mul_f32 v[200:201], v[134:135], v[196:197]
	v_pk_fma_f32 v[210:211], v[132:133], v[202:203], v[192:193] neg_lo:[0,0,1] neg_hi:[0,0,1]
	v_pk_mul_f32 v[192:193], v[136:137], v[202:203]
	v_pk_mul_f32 v[202:203], v[134:135], v[204:205]
	v_pk_mul_f32 v[216:217], v[176:177], v[198:199] op_sel_hi:[0,1]
	v_pk_fma_f32 v[200:201], v[130:131], v[204:205], v[200:201] neg_lo:[0,0,1] neg_hi:[0,0,1]
	v_pk_fma_f32 v[204:205], v[132:133], v[194:195], v[192:193]
	v_pk_fma_f32 v[196:197], v[130:131], v[196:197], v[202:203]
	v_pk_mul_f32 v[194:195], v[176:177], v[208:209] op_sel_hi:[0,1]
	v_pk_mul_f32 v[214:215], v[176:177], v[178:179] op_sel_hi:[0,1]
	v_pk_mul_f32 v[224:225], v[54:55], v[216:217]
	v_pk_mul_f32 v[192:193], v[176:177], v[206:207] op_sel_hi:[0,1]
	v_pk_mul_f32 v[212:213], v[176:177], v[200:201] op_sel_hi:[0,1]
	v_pk_mul_f32 v[220:221], v[176:177], v[196:197] op_sel_hi:[0,1]
	v_pk_mul_f32 v[222:223], v[56:57], v[214:215]
	v_pk_fma_f32 v[224:225], v[62:63], v[194:195], v[224:225] neg_lo:[0,0,1] neg_hi:[0,0,1]
	v_pk_mul_f32 v[194:195], v[54:55], v[194:195]
	v_pk_mul_f32 v[202:203], v[176:177], v[210:211] op_sel_hi:[0,1]
	v_pk_mul_f32 v[218:219], v[176:177], v[204:205] op_sel_hi:[0,1]
	v_pk_fma_f32 v[222:223], v[64:65], v[192:193], v[222:223] neg_lo:[0,0,1] neg_hi:[0,0,1]
	v_pk_mul_f32 v[228:229], v[50:51], v[220:221]
; __device__ __forceinline__ unsigned cvt_pk_bf16(float lo, float hi) { unsigned r; asm volatile("v_cvt_pk_bf16_f32 %0, %1, %2" : "=v"(r) : "v"(lo), "v"(hi)); return r; }
;     __device__ __forceinline__ void operator()(const f32x4 (&acc)[2][2][4][2], const pg8::Unit& u, int wr, int wc, int fr, int fq) const {
;     ...
;             for (int k = 0; k < 12; ++k) {
;                 if (k < 4 || k >= 8) {
;                     const int ai = k >> 3, m = k & 3;
;                     const int row = row0 + ai * 128 + m * 16;
;                     const f32x4 c0 = c[0] * osc, c1 = c[1] * osc, s0 = sn[0] * osc, s1 = sn[1] * osc;
;                     const f32x4 a0 = acc[ai][0][m][0], a1 = acc[ai][0][m][1], b0 = acc[ai][1][m][0], b1 = acc[ai][1][m][1];
;                     const f32x4 o10 = a0 * c0 - b0 * s0, o11 = a1 * c1 - b1 * s1, o20 = a0 * s0 + b0 * c0, o21 = a1 * s1 + b1 * c1;
;                     bf16_t* rowp = base + (size_t)row * 512 + col0;
;                     u32x4 w; w.x = cvt_pk_bf16(o10[0], o10[1]); w.y = cvt_pk_bf16(o10[2], o10[3]); w.z = cvt_pk_bf16(o11[0], o11[1]); w.w = cvt_pk_bf16(o11[2], o11[3]);
;                     *(u32x4*)(rowp) = w;
;                     w.x = cvt_pk_bf16(o20[0], o20[1]); w.y = cvt_pk_bf16(o20[2], o20[3]); w.z = cvt_pk_bf16(o21[0], o21[1]); w.w = cvt_pk_bf16(o21[2], o21[3]);
;                     *(u32x4*)(rowp + 64) = w;
;                 }
;                 if (k < 11) {
; #pragma unroll
;                     for (int e = 0; e < 2; ++e) { const f32x4 cn = c[e] * c16[e] - sn[e] * s16[e]; sn[e] = sn[e] * c16[e] + c[e] * s16[e]; c[e] = cn; } }
;             }
	v_pk_mul_f32 v[192:193], v[56:57], v[192:193]
	v_pk_fma_f32 v[216:217], v[62:63], v[216:217], v[194:195]
	v_pk_mul_f32 v[194:195], v[50:51], v[212:213]
	v_pk_mul_f32 v[226:227], v[52:53], v[218:219]
	v_pk_fma_f32 v[228:229], v[58:59], v[212:213], v[228:229] neg_lo:[0,0,1] neg_hi:[0,0,1]
	v_pk_fma_f32 v[214:215], v[64:65], v[214:215], v[192:193]
	v_pk_mul_f32 v[192:193], v[52:53], v[202:203]
	v_pk_fma_f32 v[212:213], v[58:59], v[220:221], v[194:195]
	v_add_co_u32_e32 v220, vcc, s87, v174
	v_pk_fma_f32 v[226:227], v[60:61], v[202:203], v[226:227] neg_lo:[0,0,1] neg_hi:[0,0,1]
	v_pk_fma_f32 v[202:203], v[60:61], v[218:219], v[192:193]
	v_cvt_pk_bf16_f32 v192, v224, v225
	v_cvt_pk_bf16_f32 v193, v222, v223
	v_cvt_pk_bf16_f32 v194, v228, v229
	v_cvt_pk_bf16_f32 v195, v226, v227
	v_addc_co_u32_e32 v221, vcc, 0, v175, vcc
	v_lshl_add_u64 v[218:219], v[174:175], 0, s[16:17]
	global_store_dwordx4 v[220:221], v[192:195], off
	s_nop 1
	v_cvt_pk_bf16_f32 v192, v216, v217
	v_cvt_pk_bf16_f32 v193, v214, v215
	v_cvt_pk_bf16_f32 v194, v212, v213
	v_cvt_pk_bf16_f32 v195, v202, v203
	global_store_dwordx4 v[218:219], v[192:195], off offset:128
	s_nop 1
	v_pk_mul_f32 v[194:195], v[142:143], v[198:199]
	v_pk_mul_f32 v[192:193], v[144:145], v[178:179]
	v_pk_fma_f32 v[212:213], v[138:139], v[208:209], v[194:195] neg_lo:[0,0,1] neg_hi:[0,0,1]
	v_pk_mul_f32 v[194:195], v[142:143], v[208:209]
	v_pk_fma_f32 v[202:203], v[140:141], v[206:207], v[192:193] neg_lo:[0,0,1] neg_hi:[0,0,1]
	v_pk_mul_f32 v[192:193], v[144:145], v[206:207]
	v_pk_fma_f32 v[198:199], v[138:139], v[198:199], v[194:195]
	v_pk_mul_f32 v[194:195], v[134:135], v[196:197]
	v_pk_fma_f32 v[178:179], v[140:141], v[178:179], v[192:193]
	v_pk_mul_f32 v[192:193], v[136:137], v[204:205]
	v_pk_fma_f32 v[208:209], v[130:131], v[200:201], v[194:195] neg_lo:[0,0,1] neg_hi:[0,0,1]
	v_pk_mul_f32 v[194:195], v[134:135], v[200:201]
	v_pk_mul_f32 v[216:217], v[176:177], v[198:199] op_sel_hi:[0,1]
	v_pk_fma_f32 v[206:207], v[132:133], v[210:211], v[192:193] neg_lo:[0,0,1] neg_hi:[0,0,1]
	v_pk_mul_f32 v[192:193], v[136:137], v[210:211]
	v_pk_fma_f32 v[196:197], v[130:131], v[196:197], v[194:195]
	v_pk_mul_f32 v[194:195], v[176:177], v[212:213] op_sel_hi:[0,1]
	v_pk_mul_f32 v[214:215], v[176:177], v[178:179] op_sel_hi:[0,1]
	v_pk_mul_f32 v[224:225], v[38:39], v[216:217]
	v_pk_fma_f32 v[200:201], v[132:133], v[204:205], v[192:193]
	v_pk_mul_f32 v[192:193], v[176:177], v[202:203] op_sel_hi:[0,1]
	v_pk_mul_f32 v[210:211], v[176:177], v[208:209] op_sel_hi:[0,1]
	v_pk_mul_f32 v[220:221], v[176:177], v[196:197] op_sel_hi:[0,1]
	v_pk_mul_f32 v[222:223], v[40:41], v[214:215]
	v_pk_fma_f32 v[224:225], v[46:47], v[194:195], v[224:225] neg_lo:[0,0,1] neg_hi:[0,0,1]
	v_pk_mul_f32 v[194:195], v[38:39], v[194:195]
	v_pk_mul_f32 v[204:205], v[176:177], v[206:207] op_sel_hi:[0,1]
	v_pk_mul_f32 v[218:219], v[176:177], v[200:201] op_sel_hi:[0,1]
	v_pk_fma_f32 v[222:223], v[48:49], v[192:193], v[222:223] neg_lo:[0,0,1] neg_hi:[0,0,1]
	v_pk_mul_f32 v[228:229], v[34:35], v[220:221]
	v_pk_mul_f32 v[192:193], v[40:41], v[192:193]
	v_pk_fma_f32 v[216:217], v[46:47], v[216:217], v[194:195]
	v_pk_mul_f32 v[194:195], v[34:35], v[210:211]
	v_pk_mul_f32 v[226:227], v[36:37], v[218:219]
	v_pk_fma_f32 v[228:229], v[42:43], v[210:211], v[228:229] neg_lo:[0,0,1] neg_hi:[0,0,1]
	v_pk_fma_f32 v[214:215], v[48:49], v[214:215], v[192:193]
	v_pk_mul_f32 v[192:193], v[36:37], v[204:205]
	v_pk_fma_f32 v[210:211], v[42:43], v[220:221], v[194:195]
	v_add_co_u32_e32 v220, vcc, s88, v174
	v_pk_fma_f32 v[226:227], v[44:45], v[204:205], v[226:227] neg_lo:[0,0,1] neg_hi:[0,0,1]
	v_pk_fma_f32 v[204:205], v[44:45], v[218:219], v[192:193]
	v_cvt_pk_bf16_f32 v192, v224, v225
	v_cvt_pk_bf16_f32 v193, v222, v223
	v_cvt_pk_bf16_f32 v194, v228, v229
	v_cvt_pk_bf16_f32 v195, v226, v227
	v_addc_co_u32_e32 v221, vcc, 0, v175, vcc
	v_lshl_add_u64 v[218:219], v[174:175], 0, s[18:19]
	global_store_dwordx4 v[220:221], v[192:195], off
	s_nop 1
	v_cvt_pk_bf16_f32 v192, v216, v217
	v_cvt_pk_bf16_f32 v193, v214, v215
	v_cvt_pk_bf16_f32 v194, v210, v211
	v_cvt_pk_bf16_f32 v195, v204, v205
	global_store_dwordx4 v[218:219], v[192:195], off offset:128
	s_nop 1
	v_pk_mul_f32 v[194:195], v[142:143], v[198:199]
	v_pk_mul_f32 v[192:193], v[144:145], v[178:179]
	v_pk_fma_f32 v[210:211], v[138:139], v[212:213], v[194:195] neg_lo:[0,0,1] neg_hi:[0,0,1]
	v_pk_mul_f32 v[194:195], v[142:143], v[212:213]
	v_pk_fma_f32 v[204:205], v[140:141], v[202:203], v[192:193] neg_lo:[0,0,1] neg_hi:[0,0,1]
	v_pk_mul_f32 v[192:193], v[144:145], v[202:203]
	v_pk_fma_f32 v[198:199], v[138:139], v[198:199], v[194:195]
	v_pk_mul_f32 v[194:195], v[134:135], v[196:197]
	v_pk_fma_f32 v[178:179], v[140:141], v[178:179], v[192:193]
	v_pk_mul_f32 v[192:193], v[136:137], v[200:201]
	v_pk_fma_f32 v[212:213], v[130:131], v[208:209], v[194:195] neg_lo:[0,0,1] neg_hi:[0,0,1]
	v_pk_mul_f32 v[194:195], v[134:135], v[208:209]
	v_pk_mul_f32 v[216:217], v[176:177], v[198:199] op_sel_hi:[0,1]
	v_pk_fma_f32 v[202:203], v[132:133], v[206:207], v[192:193] neg_lo:[0,0,1] neg_hi:[0,0,1]
	v_pk_mul_f32 v[192:193], v[136:137], v[206:207]
; __device__ __forceinline__ unsigned cvt_pk_bf16(float lo, float hi) { unsigned r; asm volatile("v_cvt_pk_bf16_f32 %0, %1, %2" : "=v"(r) : "v"(lo), "v"(hi)); return r; }
;     __device__ __forceinline__ void operator()(const f32x4 (&acc)[2][2][4][2], const pg8::Unit& u, int wr, int wc, int fr, int fq) const {
;     ...
;             for (int k = 0; k < 12; ++k) {
;                 if (k < 4 || k >= 8) {
;                     const int ai = k >> 3, m = k & 3;
;                     const int row = row0 + ai * 128 + m * 16;
;                     const f32x4 c0 = c[0] * osc, c1 = c[1] * osc, s0 = sn[0] * osc, s1 = sn[1] * osc;
;                     const f32x4 a0 = acc[ai][0][m][0], a1 = acc[ai][0][m][1], b0 = acc[ai][1][m][0], b1 = acc[ai][1][m][1];
;                     const f32x4 o10 = a0 * c0 - b0 * s0, o11 = a1 * c1 - b1 * s1, o20 = a0 * s0 + b0 * c0, o21 = a1 * s1 + b1 * c1;
;                     bf16_t* rowp = base + (size_t)row * 512 + col0;
;                     u32x4 w; w.x = cvt_pk_bf16(o10[0], o10[1]); w.y = cvt_pk_bf16(o10[2], o10[3]); w.z = cvt_pk_bf16(o11[0], o11[1]); w.w = cvt_pk_bf16(o11[2], o11[3]);
;                     *(u32x4*)(rowp) = w;
;                     w.x = cvt_pk_bf16(o20[0], o20[1]); w.y = cvt_pk_bf16(o20[2], o20[3]); w.z = cvt_pk_bf16(o21[0], o21[1]); w.w = cvt_pk_bf16(o21[2], o21[3]);
;                     *(u32x4*)(rowp + 64) = w;
;                 }
;                 if (k < 11) {
; #pragma unroll
;                     for (int e = 0; e < 2; ++e) { const f32x4 cn = c[e] * c16[e] - sn[e] * s16[e]; sn[e] = sn[e] * c16[e] + c[e] * s16[e]; c[e] = cn; } }
;             }
	v_pk_fma_f32 v[196:197], v[130:131], v[196:197], v[194:195]
	v_pk_mul_f32 v[194:195], v[176:177], v[210:211] op_sel_hi:[0,1]
	v_pk_mul_f32 v[214:215], v[176:177], v[178:179] op_sel_hi:[0,1]
	v_pk_mul_f32 v[224:225], v[22:23], v[216:217]
	v_pk_fma_f32 v[200:201], v[132:133], v[200:201], v[192:193]
	v_pk_mul_f32 v[192:193], v[176:177], v[204:205] op_sel_hi:[0,1]
	v_pk_mul_f32 v[208:209], v[176:177], v[212:213] op_sel_hi:[0,1]
	v_pk_mul_f32 v[220:221], v[176:177], v[196:197] op_sel_hi:[0,1]
	v_pk_mul_f32 v[222:223], v[24:25], v[214:215]
	v_pk_fma_f32 v[224:225], v[30:31], v[194:195], v[224:225] neg_lo:[0,0,1] neg_hi:[0,0,1]
	v_pk_mul_f32 v[194:195], v[22:23], v[194:195]
	v_pk_mul_f32 v[206:207], v[176:177], v[202:203] op_sel_hi:[0,1]
	v_pk_mul_f32 v[218:219], v[176:177], v[200:201] op_sel_hi:[0,1]
	v_pk_fma_f32 v[222:223], v[32:33], v[192:193], v[222:223] neg_lo:[0,0,1] neg_hi:[0,0,1]
	v_pk_mul_f32 v[228:229], v[18:19], v[220:221]
	v_pk_mul_f32 v[192:193], v[24:25], v[192:193]
	v_pk_fma_f32 v[216:217], v[30:31], v[216:217], v[194:195]
	v_pk_mul_f32 v[194:195], v[18:19], v[208:209]
	v_pk_mul_f32 v[226:227], v[20:21], v[218:219]
	v_pk_fma_f32 v[228:229], v[26:27], v[208:209], v[228:229] neg_lo:[0,0,1] neg_hi:[0,0,1]
	v_pk_fma_f32 v[214:215], v[32:33], v[214:215], v[192:193]
	v_pk_mul_f32 v[192:193], v[20:21], v[206:207]
	v_pk_fma_f32 v[208:209], v[26:27], v[220:221], v[194:195]
	v_add_co_u32_e32 v220, vcc, s89, v174
	v_pk_fma_f32 v[226:227], v[28:29], v[206:207], v[226:227] neg_lo:[0,0,1] neg_hi:[0,0,1]
	v_pk_fma_f32 v[206:207], v[28:29], v[218:219], v[192:193]
	v_cvt_pk_bf16_f32 v192, v224, v225
	v_cvt_pk_bf16_f32 v193, v222, v223
	v_cvt_pk_bf16_f32 v194, v228, v229
	v_cvt_pk_bf16_f32 v195, v226, v227
	v_addc_co_u32_e32 v221, vcc, 0, v175, vcc
	v_lshl_add_u64 v[218:219], v[174:175], 0, s[20:21]
	global_store_dwordx4 v[220:221], v[192:195], off
	s_nop 1
	v_cvt_pk_bf16_f32 v192, v216, v217
	v_cvt_pk_bf16_f32 v193, v214, v215
	v_cvt_pk_bf16_f32 v194, v208, v209
	v_cvt_pk_bf16_f32 v195, v206, v207
	global_store_dwordx4 v[218:219], v[192:195], off offset:128
	s_nop 1
	v_pk_mul_f32 v[192:193], v[144:145], v[178:179]
	v_pk_mul_f32 v[194:195], v[142:143], v[198:199]
	v_pk_mul_f32 v[144:145], v[144:145], v[204:205]
	v_pk_mul_f32 v[142:143], v[142:143], v[210:211]
	v_pk_fma_f32 v[192:193], v[140:141], v[204:205], v[192:193] neg_lo:[0,0,1] neg_hi:[0,0,1]
	v_pk_fma_f32 v[194:195], v[138:139], v[210:211], v[194:195] neg_lo:[0,0,1] neg_hi:[0,0,1]
	v_pk_fma_f32 v[140:141], v[140:141], v[178:179], v[144:145]
	v_pk_fma_f32 v[138:139], v[138:139], v[198:199], v[142:143]
	v_pk_mul_f32 v[142:143], v[136:137], v[200:201]
	v_pk_mul_f32 v[144:145], v[134:135], v[196:197]
	v_pk_mul_f32 v[136:137], v[136:137], v[202:203]
	v_pk_mul_f32 v[134:135], v[134:135], v[212:213]
	v_pk_fma_f32 v[142:143], v[132:133], v[202:203], v[142:143] neg_lo:[0,0,1] neg_hi:[0,0,1]
	v_pk_fma_f32 v[144:145], v[130:131], v[212:213], v[144:145] neg_lo:[0,0,1] neg_hi:[0,0,1]
	v_pk_fma_f32 v[132:133], v[132:133], v[200:201], v[136:137]
	v_pk_fma_f32 v[130:131], v[130:131], v[196:197], v[134:135]
	v_pk_mul_f32 v[140:141], v[176:177], v[140:141] op_sel_hi:[0,1]
	v_pk_mul_f32 v[138:139], v[176:177], v[138:139] op_sel_hi:[0,1]
	v_pk_mul_f32 v[134:135], v[176:177], v[192:193] op_sel_hi:[0,1]
	v_pk_mul_f32 v[136:137], v[176:177], v[194:195] op_sel_hi:[0,1]
	v_pk_mul_f32 v[142:143], v[176:177], v[142:143] op_sel_hi:[0,1]
	v_pk_mul_f32 v[144:145], v[176:177], v[144:145] op_sel_hi:[0,1]
	v_pk_mul_f32 v[132:133], v[176:177], v[132:133] op_sel_hi:[0,1]
	v_pk_mul_f32 v[130:131], v[176:177], v[130:131] op_sel_hi:[0,1]
	v_pk_mul_f32 v[176:177], v[8:9], v[140:141]
	v_pk_mul_f32 v[178:179], v[6:7], v[138:139]
	v_pk_fma_f32 v[176:177], v[16:17], v[134:135], v[176:177] neg_lo:[0,0,1] neg_hi:[0,0,1]
	v_pk_fma_f32 v[178:179], v[14:15], v[136:137], v[178:179] neg_lo:[0,0,1] neg_hi:[0,0,1]
	v_pk_mul_f32 v[194:195], v[2:3], v[130:131]
	v_pk_mul_f32 v[134:135], v[8:9], v[134:135]
	v_pk_mul_f32 v[136:137], v[6:7], v[136:137]
	v_pk_mul_f32 v[192:193], v[4:5], v[132:133]
	v_pk_fma_f32 v[194:195], v[10:11], v[144:145], v[194:195] neg_lo:[0,0,1] neg_hi:[0,0,1]
	v_pk_fma_f32 v[134:135], v[16:17], v[140:141], v[134:135]
	v_pk_fma_f32 v[136:137], v[14:15], v[138:139], v[136:137]
	v_pk_mul_f32 v[138:139], v[4:5], v[142:143]
	v_pk_mul_f32 v[140:141], v[2:3], v[144:145]
	v_add_co_u32_e32 v144, vcc, s90, v174
	v_pk_fma_f32 v[192:193], v[12:13], v[142:143], v[192:193] neg_lo:[0,0,1] neg_hi:[0,0,1]
	v_pk_fma_f32 v[138:139], v[12:13], v[132:133], v[138:139]
	v_pk_fma_f32 v[140:141], v[10:11], v[130:131], v[140:141]
	v_lshl_add_u64 v[142:143], v[174:175], 0, s[24:25]
	v_cvt_pk_bf16_f32 v130, v178, v179
	v_cvt_pk_bf16_f32 v131, v176, v177
	v_cvt_pk_bf16_f32 v132, v194, v195
	v_cvt_pk_bf16_f32 v133, v192, v193
	v_addc_co_u32_e32 v145, vcc, 0, v175, vcc
	global_store_dwordx4 v[144:145], v[130:133], off
	s_nop 1
	v_cvt_pk_bf16_f32 v130, v136, v137
	v_cvt_pk_bf16_f32 v131, v134, v135
	v_cvt_pk_bf16_f32 v132, v140, v141
	v_cvt_pk_bf16_f32 v133, v138, v139
	global_store_dwordx4 v[142:143], v[130:133], off offset:128

; __device__ __forceinline__ unsigned cvt_pk_bf16(float lo, float hi) { unsigned r; asm volatile("v_cvt_pk_bf16_f32 %0, %1, %2" : "=v"(r) : "v"(lo), "v"(hi)); return r; }
;     __device__ __forceinline__ void operator()(const f32x4 (&acc)[2][2][4][2], const pg8::Unit& u, int wr, int wc, int fr, int fq) const {
;     ...
;         if (sec <= 1) {
;             const float* gn = sec == 0 ? qg : kg; const float osc = sec == 0 ? 0.125f * LOG2E : 1.f;
;             f32x4 g[2][2];
; #pragma unroll
;             for (int bj = 0; bj < 2; ++bj)
; #pragma unroll
;                 for (int n = 0; n < 2; ++n) g[bj][n] = *(const f32x4*)(gn + 32 * bj + 8 * fq + 4 * n);
;             const int col0 = 256 * half + 64 * wc + 8 * fq;
; #pragma unroll
;             for (int ai = 0; ai < 2; ++ai)
; #pragma unroll
;                 for (int m = 0; m < 4; ++m) {
;                     float ss = 0.f;
; #pragma unroll
;                     for (int bj = 0; bj < 2; ++bj)
; #pragma unroll
;                         for (int n = 0; n < 2; ++n) { const f32x4 x = acc[ai][bj][m][n]; ss += (x[0] * x[0] + x[1] * x[1]) + (x[2] * x[2] + x[3] * x[3]); }
;                     ss = row4_sum(ss);
;                     const float r = rsqrtf(ss * (1.f / 64.f) + EPS) * osc;
;                     bf16_t* rowp = base + (size_t)(row0 + ai * 128 + m * 16) * 512 + col0;
; #pragma unroll
;                     for (int bj = 0; bj < 2; ++bj) { const f32x4 v0 = acc[ai][bj][m][0] * r * g[bj][0], v1 = acc[ai][bj][m][1] * r * g[bj][1];
;                         u32x4 w; w.x = cvt_pk_bf16(v0[0], v0[1]); w.y = cvt_pk_bf16(v0[2], v0[3]); w.z = cvt_pk_bf16(v1[0], v1[1]); w.w = cvt_pk_bf16(v1[2], v1[3]);
;                         *(u32x4*)(rowp + 32 * bj) = w; }
;                 }
.LBB0_205:
	s_cmp_lt_u32 s46, 2
	s_cselect_b64 vcc, -1, 0
	s_and_b64 s[4:5], vcc, exec
	s_cselect_b32 s5, s53, s55
	s_cselect_b32 s4, s52, s54
	global_load_dwordx4 v[142:145], v187, s[4:5]
	global_load_dwordx4 v[138:141], v187, s[4:5] offset:16
	global_load_dwordx4 v[134:137], v187, s[4:5] offset:128
	global_load_dwordx4 v[130:133], v187, s[4:5] offset:144
	s_mov_b32 s4, 0x55555555
	s_mov_b32 s5, 0x55555555
	v_and_b32_e32 v218, 1, v172
	v_sub_u32_e32 v219, 0, v218
	v_and_b32_e32 v218, 0xfffffc40, v219
	v_mul_f32_e32 v176, v127, v127
	v_mul_f32_e32 v177, v129, v129
	v_mul_f32_e32 v179, v123, v123
	v_mul_f32_e32 v191, v125, v125
	v_mul_f32_e32 v192, v119, v119
	v_mul_f32_e32 v193, v121, v121
	v_ashrrev_i32_e32 v173, 31, v172
	v_fmac_f32_e32 v176, v126, v126
	v_fmac_f32_e32 v177, v128, v128
	v_fmac_f32_e32 v179, v122, v122
	v_fmac_f32_e32 v191, v124, v124
	v_mul_f32_e32 v194, v115, v115
	v_mul_f32_e32 v195, v117, v117
	v_fmac_f32_e32 v192, v118, v118
	v_fmac_f32_e32 v193, v120, v120
	v_lshlrev_b64 v[174:175], 10, v[172:173]
	v_add_f32_e32 v173, v176, v177
	v_add_f32_e32 v176, v179, v191
	v_fmac_f32_e32 v194, v114, v114
	v_fmac_f32_e32 v195, v116, v116
	v_add_f32_e32 v177, v192, v193
	v_add_f32_e32 v173, v173, v176
	v_add_f32_e32 v179, v194, v195
	v_add_f32_e32 v173, v173, v177
	v_add_f32_e32 v173, v173, v179
	v_mov_b32_e32 v176, v173
	s_nop 1
	v_permlane16_swap_b32_e32 v173, v176
	v_add_f32_e32 v173, v173, v176
	v_mov_b32_e32 v176, v173
	s_nop 1
	v_permlane32_swap_b32_e32 v173, v176
	v_add_f32_e32 v173, v173, v176
	v_fmamk_f32 v173, v173, 0x3c800000, v188
	v_cndmask_b32_e32 v178, 1.0, v190, vcc
	v_mul_f32_e32 v176, 0x4b800000, v173
	v_cmp_gt_f32_e32 vcc, s91, v173
	v_lshlrev_b32_e32 v154, 1, v182
	v_lshl_or_b32 v154, s27, 9, v154
	v_cndmask_b32_e32 v173, v173, v176, vcc
	v_rsq_f32_e32 v173, v173
	v_lshl_add_u64 v[176:177], s[48:49], 0, v[154:155]
	v_mul_f32_e32 v196, v111, v111
	v_mul_f32_e32 v197, v113, v113
	v_mul_f32_e32 v154, 0x45800000, v173
	v_cndmask_b32_e32 v154, v173, v154, vcc
	v_mul_f32_e32 v154, v178, v154
	v_pk_mul_f32 v[126:127], v[126:127], v[154:155] op_sel_hi:[1,0]
	v_pk_mul_f32 v[128:129], v[128:129], v[154:155] op_sel_hi:[1,0]
	v_pk_mul_f32 v[122:123], v[122:123], v[154:155] op_sel_hi:[1,0]
	v_pk_mul_f32 v[124:125], v[124:125], v[154:155] op_sel_hi:[1,0]
	v_pk_mul_f32 v[118:119], v[118:119], v[154:155] op_sel_hi:[1,0]
	v_pk_mul_f32 v[114:115], v[114:115], v[154:155] op_sel_hi:[1,0]
	v_pk_mul_f32 v[116:117], v[116:117], v[154:155] op_sel_hi:[1,0]
	v_mul_f32_e32 v198, v107, v107
	v_mul_f32_e32 v199, v109, v109
	v_lshl_add_u64 v[174:175], v[176:177], 0, v[174:175]
	v_fmac_f32_e32 v196, v110, v110
	v_fmac_f32_e32 v197, v112, v112
	v_fmac_f32_e32 v198, v106, v106
	v_fmac_f32_e32 v199, v108, v108
	v_add_f32_e32 v179, v196, v197
	v_pk_mul_f32 v[120:121], v[120:121], v[154:155] op_sel_hi:[1,0]
	s_waitcnt vmcnt(0)
	v_pk_mul_f32 v[128:129], v[144:145], v[128:129]
	v_pk_mul_f32 v[126:127], v[142:143], v[126:127]
	v_pk_mul_f32 v[124:125], v[140:141], v[124:125]
	v_pk_mul_f32 v[122:123], v[138:139], v[122:123]
	v_pk_mul_f32 v[118:119], v[134:135], v[118:119]
	v_pk_mul_f32 v[192:193], v[132:133], v[116:117]
	v_pk_mul_f32 v[194:195], v[130:131], v[114:115]
	v_cvt_pk_bf16_f32 v114, v126, v127
	v_cvt_pk_bf16_f32 v115, v128, v129
	v_cvt_pk_bf16_f32 v116, v122, v123
	v_cvt_pk_bf16_f32 v117, v124, v125
	v_mov_b32_e32 v200, v114
	v_mov_b32_e32 v201, v115
	v_mov_b32_e32 v202, v116
	v_mov_b32_e32 v203, v117
	v_lshl_add_u64 v[216:217], v[174:175], 0, v[218:219]
	v_pk_mul_f32 v[120:121], v[136:137], v[120:121]
	s_nop 0
	v_cvt_pk_bf16_f32 v114, v118, v119
	v_mul_f32_e32 v117, v103, v103
	v_mul_f32_e32 v118, v105, v105
	v_add_f32_e32 v116, v198, v199
	v_fmac_f32_e32 v117, v102, v102
	v_fmac_f32_e32 v118, v104, v104
	v_add_f32_e32 v116, v179, v116
	v_add_f32_e32 v117, v117, v118
	v_add_f32_e32 v116, v116, v117
	v_mul_f32_e32 v117, v99, v99
	v_mul_f32_e32 v118, v101, v101
	v_fmac_f32_e32 v117, v98, v98
	v_fmac_f32_e32 v118, v100, v100
	v_add_f32_e32 v117, v117, v118
	v_add_f32_e32 v116, v116, v117
	v_mov_b32_e32 v117, v116
	s_nop 1
	v_permlane16_swap_b32_e32 v116, v117
	v_add_f32_e32 v116, v116, v117
	v_mov_b32_e32 v117, v116
	s_nop 1
	v_permlane32_swap_b32_e32 v116, v117
	v_add_f32_e32 v116, v116, v117
	v_fmamk_f32 v116, v116, 0x3c800000, v188
	v_mul_f32_e32 v117, 0x4b800000, v116
	v_cmp_gt_f32_e32 vcc, s91, v116
	v_cvt_pk_bf16_f32 v115, v120, v121
	s_nop 1
	v_cndmask_b32_e32 v116, v116, v117, vcc
	v_rsq_f32_e32 v118, v116
	v_cvt_pk_bf16_f32 v116, v194, v195
	v_cvt_pk_bf16_f32 v117, v192, v193
	v_mov_b32_dpp v212, v200 quad_perm:[1,0,3,2] row_mask:0xf bank_mask:0xf
	v_mov_b32_dpp v213, v201 quad_perm:[1,0,3,2] row_mask:0xf bank_mask:0xf
	v_mov_b32_dpp v214, v202 quad_perm:[1,0,3,2] row_mask:0xf bank_mask:0xf
	v_mov_b32_dpp v215, v203 quad_perm:[1,0,3,2] row_mask:0xf bank_mask:0xf
	v_mov_b32_dpp v204, v114 quad_perm:[1,0,3,2] row_mask:0xf bank_mask:0xf
	v_mov_b32_dpp v205, v115 quad_perm:[1,0,3,2] row_mask:0xf bank_mask:0xf
	v_mov_b32_dpp v206, v116 quad_perm:[1,0,3,2] row_mask:0xf bank_mask:0xf
	v_mov_b32_dpp v207, v117 quad_perm:[1,0,3,2] row_mask:0xf bank_mask:0xf
	v_cndmask_b32_e64 v212, v114, v212, s[4:5]
	v_cndmask_b32_e64 v213, v115, v213, s[4:5]
	v_cndmask_b32_e64 v214, v116, v214, s[4:5]
	v_cndmask_b32_e64 v215, v117, v215, s[4:5]
	v_cndmask_b32_e64 v208, v204, v200, s[4:5]
	v_cndmask_b32_e64 v209, v205, v201, s[4:5]
	v_cndmask_b32_e64 v210, v206, v202, s[4:5]
	v_cndmask_b32_e64 v211, v207, v203, s[4:5]
	global_store_dwordx4 v[216:217], v[208:211], off
	global_store_dwordx4 v[216:217], v[212:215], off offset:1024
	s_nop 1
; __device__ __forceinline__ unsigned cvt_pk_bf16(float lo, float hi) { unsigned r; asm volatile("v_cvt_pk_bf16_f32 %0, %1, %2" : "=v"(r) : "v"(lo), "v"(hi)); return r; }
;     __device__ __forceinline__ void operator()(const f32x4 (&acc)[2][2][4][2], const pg8::Unit& u, int wr, int wc, int fr, int fq) const {
;     ...
;         if (sec <= 1) {
;             const float* gn = sec == 0 ? qg : kg; const float osc = sec == 0 ? 0.125f * LOG2E : 1.f;
;             f32x4 g[2][2];
; #pragma unroll
;             for (int bj = 0; bj < 2; ++bj)
; #pragma unroll
;                 for (int n = 0; n < 2; ++n) g[bj][n] = *(const f32x4*)(gn + 32 * bj + 8 * fq + 4 * n);
;             const int col0 = 256 * half + 64 * wc + 8 * fq;
; #pragma unroll
;             for (int ai = 0; ai < 2; ++ai)
; #pragma unroll
;                 for (int m = 0; m < 4; ++m) {
;                     float ss = 0.f;
; #pragma unroll
;                     for (int bj = 0; bj < 2; ++bj)
; #pragma unroll
;                         for (int n = 0; n < 2; ++n) { const f32x4 x = acc[ai][bj][m][n]; ss += (x[0] * x[0] + x[1] * x[1]) + (x[2] * x[2] + x[3] * x[3]); }
;                     ss = row4_sum(ss);
;                     const float r = rsqrtf(ss * (1.f / 64.f) + EPS) * osc;
;                     bf16_t* rowp = base + (size_t)(row0 + ai * 128 + m * 16) * 512 + col0;
; #pragma unroll
;                     for (int bj = 0; bj < 2; ++bj) { const f32x4 v0 = acc[ai][bj][m][0] * r * g[bj][0], v1 = acc[ai][bj][m][1] * r * g[bj][1];
;                         u32x4 w; w.x = cvt_pk_bf16(v0[0], v0[1]); w.y = cvt_pk_bf16(v0[2], v0[3]); w.z = cvt_pk_bf16(v1[0], v1[1]); w.w = cvt_pk_bf16(v1[2], v1[3]);
;                         *(u32x4*)(rowp + 32 * bj) = w; }
;                 }
	v_mul_f32_e32 v114, 0x45800000, v118
	v_cndmask_b32_e32 v114, v118, v114, vcc
	v_or_b32_e32 v116, 16, v172
	v_mul_f32_e32 v114, v178, v114
	v_ashrrev_i32_e32 v117, 31, v116
	v_lshlrev_b64 v[116:117], 10, v[116:117]
	v_pk_mul_f32 v[110:111], v[110:111], v[114:115] op_sel_hi:[1,0]
	v_pk_mul_f32 v[112:113], v[112:113], v[114:115] op_sel_hi:[1,0]
	v_pk_mul_f32 v[106:107], v[106:107], v[114:115] op_sel_hi:[1,0]
	v_pk_mul_f32 v[108:109], v[108:109], v[114:115] op_sel_hi:[1,0]
	v_pk_mul_f32 v[102:103], v[102:103], v[114:115] op_sel_hi:[1,0]
	v_lshl_add_u64 v[116:117], v[176:177], 0, v[116:117]
	v_pk_mul_f32 v[112:113], v[144:145], v[112:113]
	v_pk_mul_f32 v[110:111], v[142:143], v[110:111]
	v_pk_mul_f32 v[118:119], v[140:141], v[108:109]
	v_pk_mul_f32 v[108:109], v[138:139], v[106:107]
	v_cvt_pk_bf16_f32 v106, v110, v111
	v_cvt_pk_bf16_f32 v107, v112, v113
	v_pk_mul_f32 v[102:103], v[134:135], v[102:103]
	v_pk_mul_f32 v[98:99], v[98:99], v[114:115] op_sel_hi:[1,0]
	v_pk_mul_f32 v[100:101], v[100:101], v[114:115] op_sel_hi:[1,0]
	v_cvt_pk_bf16_f32 v108, v108, v109
	v_cvt_pk_bf16_f32 v109, v118, v119
	v_mov_b32_e32 v200, v106
	v_mov_b32_e32 v201, v107
	v_mov_b32_e32 v202, v108
	v_mov_b32_e32 v203, v109
	v_lshl_add_u64 v[216:217], v[116:117], 0, v[218:219]
	v_pk_mul_f32 v[104:105], v[104:105], v[114:115] op_sel_hi:[1,0]
	s_nop 0
	v_pk_mul_f32 v[106:107], v[132:133], v[100:101]
	v_pk_mul_f32 v[100:101], v[130:131], v[98:99]
	v_cvt_pk_bf16_f32 v98, v102, v103
	v_mul_f32_e32 v102, v95, v95
	v_mul_f32_e32 v103, v97, v97
	v_pk_mul_f32 v[104:105], v[136:137], v[104:105]
	v_fmac_f32_e32 v102, v94, v94
	v_fmac_f32_e32 v103, v96, v96
	v_cvt_pk_bf16_f32 v99, v104, v105
	v_add_f32_e32 v102, v102, v103
	v_mul_f32_e32 v103, v91, v91
	v_mul_f32_e32 v104, v93, v93
	v_fmac_f32_e32 v103, v90, v90
	v_fmac_f32_e32 v104, v92, v92
	v_add_f32_e32 v103, v103, v104
	v_add_f32_e32 v102, v102, v103
	v_mul_f32_e32 v103, v87, v87
	v_mul_f32_e32 v104, v89, v89
	v_fmac_f32_e32 v103, v86, v86
	v_fmac_f32_e32 v104, v88, v88
	v_add_f32_e32 v103, v103, v104
	v_add_f32_e32 v102, v102, v103
	v_mul_f32_e32 v103, v83, v83
	v_mul_f32_e32 v104, v85, v85
	v_fmac_f32_e32 v103, v82, v82
	v_fmac_f32_e32 v104, v84, v84
	v_add_f32_e32 v103, v103, v104
	v_add_f32_e32 v102, v102, v103
	v_mov_b32_e32 v103, v102
	s_nop 1
	v_permlane16_swap_b32_e32 v102, v103
	v_add_f32_e32 v102, v102, v103
	v_mov_b32_e32 v103, v102
	s_nop 1
	v_permlane32_swap_b32_e32 v102, v103
	v_add_f32_e32 v102, v102, v103
	v_fmamk_f32 v102, v102, 0x3c800000, v188
	v_mul_f32_e32 v103, 0x4b800000, v102
	v_cmp_gt_f32_e32 vcc, s91, v102
	v_cvt_pk_bf16_f32 v100, v100, v101
	v_cvt_pk_bf16_f32 v101, v106, v107
	v_mov_b32_dpp v212, v200 quad_perm:[1,0,3,2] row_mask:0xf bank_mask:0xf
	v_mov_b32_dpp v213, v201 quad_perm:[1,0,3,2] row_mask:0xf bank_mask:0xf
	v_mov_b32_dpp v214, v202 quad_perm:[1,0,3,2] row_mask:0xf bank_mask:0xf
	v_mov_b32_dpp v215, v203 quad_perm:[1,0,3,2] row_mask:0xf bank_mask:0xf
	v_mov_b32_dpp v204, v98 quad_perm:[1,0,3,2] row_mask:0xf bank_mask:0xf
	v_mov_b32_dpp v205, v99 quad_perm:[1,0,3,2] row_mask:0xf bank_mask:0xf
	v_mov_b32_dpp v206, v100 quad_perm:[1,0,3,2] row_mask:0xf bank_mask:0xf
	v_mov_b32_dpp v207, v101 quad_perm:[1,0,3,2] row_mask:0xf bank_mask:0xf
	v_cndmask_b32_e64 v212, v98, v212, s[4:5]
	v_cndmask_b32_e64 v213, v99, v213, s[4:5]
	v_cndmask_b32_e64 v214, v100, v214, s[4:5]
	v_cndmask_b32_e64 v215, v101, v215, s[4:5]
	v_cndmask_b32_e64 v208, v204, v200, s[4:5]
	v_cndmask_b32_e64 v209, v205, v201, s[4:5]
	v_cndmask_b32_e64 v210, v206, v202, s[4:5]
	v_cndmask_b32_e64 v211, v207, v203, s[4:5]
	global_store_dwordx4 v[216:217], v[208:211], off
	global_store_dwordx4 v[216:217], v[212:215], off offset:1024
	s_nop 0
	v_cndmask_b32_e32 v102, v102, v103, vcc
	v_rsq_f32_e32 v102, v102
	v_or_b32_e32 v100, 32, v172
	v_ashrrev_i32_e32 v101, 31, v100
	v_lshlrev_b64 v[100:101], 10, v[100:101]
	v_mul_f32_e32 v98, 0x45800000, v102
	v_cndmask_b32_e32 v98, v102, v98, vcc
	v_mul_f32_e32 v98, v178, v98
	v_pk_mul_f32 v[94:95], v[94:95], v[98:99] op_sel_hi:[1,0]
	v_pk_mul_f32 v[96:97], v[96:97], v[98:99] op_sel_hi:[1,0]
	v_pk_mul_f32 v[90:91], v[90:91], v[98:99] op_sel_hi:[1,0]
	v_pk_mul_f32 v[92:93], v[92:93], v[98:99] op_sel_hi:[1,0]
	v_pk_mul_f32 v[86:87], v[86:87], v[98:99] op_sel_hi:[1,0]
	v_lshl_add_u64 v[100:101], v[176:177], 0, v[100:101]
	v_pk_mul_f32 v[96:97], v[144:145], v[96:97]
	v_pk_mul_f32 v[94:95], v[142:143], v[94:95]
	v_pk_mul_f32 v[102:103], v[140:141], v[92:93]
	v_pk_mul_f32 v[92:93], v[138:139], v[90:91]
	v_cvt_pk_bf16_f32 v90, v94, v95
	v_cvt_pk_bf16_f32 v91, v96, v97
	v_pk_mul_f32 v[86:87], v[134:135], v[86:87]
	v_pk_mul_f32 v[82:83], v[82:83], v[98:99] op_sel_hi:[1,0]
	v_pk_mul_f32 v[84:85], v[84:85], v[98:99] op_sel_hi:[1,0]
	v_cvt_pk_bf16_f32 v92, v92, v93
	v_cvt_pk_bf16_f32 v93, v102, v103
	v_mov_b32_e32 v200, v90
	v_mov_b32_e32 v201, v91
	v_mov_b32_e32 v202, v92
	v_mov_b32_e32 v203, v93
	v_lshl_add_u64 v[216:217], v[100:101], 0, v[218:219]
	v_pk_mul_f32 v[88:89], v[88:89], v[98:99] op_sel_hi:[1,0]
	s_nop 0
	v_pk_mul_f32 v[90:91], v[132:133], v[84:85]
	v_pk_mul_f32 v[84:85], v[130:131], v[82:83]
	v_cvt_pk_bf16_f32 v82, v86, v87
	v_mul_f32_e32 v86, v79, v79
	v_mul_f32_e32 v87, v81, v81
	v_pk_mul_f32 v[88:89], v[136:137], v[88:89]
	v_fmac_f32_e32 v86, v78, v78
	v_fmac_f32_e32 v87, v80, v80
	v_cvt_pk_bf16_f32 v83, v88, v89
	v_add_f32_e32 v86, v86, v87
	v_mul_f32_e32 v87, v75, v75
	v_mul_f32_e32 v88, v77, v77
	v_fmac_f32_e32 v87, v74, v74
	v_fmac_f32_e32 v88, v76, v76
	v_add_f32_e32 v87, v87, v88
	v_add_f32_e32 v86, v86, v87
	v_mul_f32_e32 v87, v71, v71
	v_mul_f32_e32 v88, v73, v73
; __device__ __forceinline__ unsigned cvt_pk_bf16(float lo, float hi) { unsigned r; asm volatile("v_cvt_pk_bf16_f32 %0, %1, %2" : "=v"(r) : "v"(lo), "v"(hi)); return r; }
;     __device__ __forceinline__ void operator()(const f32x4 (&acc)[2][2][4][2], const pg8::Unit& u, int wr, int wc, int fr, int fq) const {
;     ...
;         if (sec <= 1) {
;             const float* gn = sec == 0 ? qg : kg; const float osc = sec == 0 ? 0.125f * LOG2E : 1.f;
;             f32x4 g[2][2];
; #pragma unroll
;             for (int bj = 0; bj < 2; ++bj)
; #pragma unroll
;                 for (int n = 0; n < 2; ++n) g[bj][n] = *(const f32x4*)(gn + 32 * bj + 8 * fq + 4 * n);
;             const int col0 = 256 * half + 64 * wc + 8 * fq;
; #pragma unroll
;             for (int ai = 0; ai < 2; ++ai)
; #pragma unroll
;                 for (int m = 0; m < 4; ++m) {
;                     float ss = 0.f;
; #pragma unroll
;                     for (int bj = 0; bj < 2; ++bj)
; #pragma unroll
;                         for (int n = 0; n < 2; ++n) { const f32x4 x = acc[ai][bj][m][n]; ss += (x[0] * x[0] + x[1] * x[1]) + (x[2] * x[2] + x[3] * x[3]); }
;                     ss = row4_sum(ss);
;                     const float r = rsqrtf(ss * (1.f / 64.f) + EPS) * osc;
;                     bf16_t* rowp = base + (size_t)(row0 + ai * 128 + m * 16) * 512 + col0;
; #pragma unroll
;                     for (int bj = 0; bj < 2; ++bj) { const f32x4 v0 = acc[ai][bj][m][0] * r * g[bj][0], v1 = acc[ai][bj][m][1] * r * g[bj][1];
;                         u32x4 w; w.x = cvt_pk_bf16(v0[0], v0[1]); w.y = cvt_pk_bf16(v0[2], v0[3]); w.z = cvt_pk_bf16(v1[0], v1[1]); w.w = cvt_pk_bf16(v1[2], v1[3]);
;                         *(u32x4*)(rowp + 32 * bj) = w; }
;                 }
	v_fmac_f32_e32 v87, v70, v70
	v_fmac_f32_e32 v88, v72, v72
	v_add_f32_e32 v87, v87, v88
	v_add_f32_e32 v86, v86, v87
	v_mul_f32_e32 v87, v67, v67
	v_mul_f32_e32 v88, v69, v69
	v_fmac_f32_e32 v87, v66, v66
	v_fmac_f32_e32 v88, v68, v68
	v_add_f32_e32 v87, v87, v88
	v_add_f32_e32 v86, v86, v87
	v_mov_b32_e32 v87, v86
	s_nop 1
	v_permlane16_swap_b32_e32 v86, v87
	v_add_f32_e32 v86, v86, v87
	v_mov_b32_e32 v87, v86
	s_nop 1
	v_permlane32_swap_b32_e32 v86, v87
	v_add_f32_e32 v86, v86, v87
	v_fmamk_f32 v86, v86, 0x3c800000, v188
	v_mul_f32_e32 v87, 0x4b800000, v86
	v_cmp_gt_f32_e32 vcc, s91, v86
	v_cvt_pk_bf16_f32 v84, v84, v85
	v_cvt_pk_bf16_f32 v85, v90, v91
	v_mov_b32_dpp v212, v200 quad_perm:[1,0,3,2] row_mask:0xf bank_mask:0xf
	v_mov_b32_dpp v213, v201 quad_perm:[1,0,3,2] row_mask:0xf bank_mask:0xf
	v_mov_b32_dpp v214, v202 quad_perm:[1,0,3,2] row_mask:0xf bank_mask:0xf
	v_mov_b32_dpp v215, v203 quad_perm:[1,0,3,2] row_mask:0xf bank_mask:0xf
	v_mov_b32_dpp v204, v82 quad_perm:[1,0,3,2] row_mask:0xf bank_mask:0xf
	v_mov_b32_dpp v205, v83 quad_perm:[1,0,3,2] row_mask:0xf bank_mask:0xf
	v_mov_b32_dpp v206, v84 quad_perm:[1,0,3,2] row_mask:0xf bank_mask:0xf
	v_mov_b32_dpp v207, v85 quad_perm:[1,0,3,2] row_mask:0xf bank_mask:0xf
	v_cndmask_b32_e64 v212, v82, v212, s[4:5]
	v_cndmask_b32_e64 v213, v83, v213, s[4:5]
	v_cndmask_b32_e64 v214, v84, v214, s[4:5]
	v_cndmask_b32_e64 v215, v85, v215, s[4:5]
	v_cndmask_b32_e64 v208, v204, v200, s[4:5]
	v_cndmask_b32_e64 v209, v205, v201, s[4:5]
	v_cndmask_b32_e64 v210, v206, v202, s[4:5]
	v_cndmask_b32_e64 v211, v207, v203, s[4:5]
	global_store_dwordx4 v[216:217], v[208:211], off
	global_store_dwordx4 v[216:217], v[212:215], off offset:1024
	s_nop 0
	v_cndmask_b32_e32 v86, v86, v87, vcc
	v_rsq_f32_e32 v86, v86
	v_or_b32_e32 v84, 48, v172
	v_ashrrev_i32_e32 v85, 31, v84
	v_lshlrev_b64 v[84:85], 10, v[84:85]
	v_mul_f32_e32 v82, 0x45800000, v86
	v_cndmask_b32_e32 v82, v86, v82, vcc
	v_mul_f32_e32 v82, v178, v82
	v_pk_mul_f32 v[78:79], v[78:79], v[82:83] op_sel_hi:[1,0]
	v_pk_mul_f32 v[80:81], v[80:81], v[82:83] op_sel_hi:[1,0]
	v_pk_mul_f32 v[74:75], v[74:75], v[82:83] op_sel_hi:[1,0]
	v_pk_mul_f32 v[76:77], v[76:77], v[82:83] op_sel_hi:[1,0]
	v_pk_mul_f32 v[70:71], v[70:71], v[82:83] op_sel_hi:[1,0]
	v_lshl_add_u64 v[84:85], v[176:177], 0, v[84:85]
	v_pk_mul_f32 v[80:81], v[144:145], v[80:81]
	v_pk_mul_f32 v[78:79], v[142:143], v[78:79]
	v_pk_mul_f32 v[86:87], v[140:141], v[76:77]
	v_pk_mul_f32 v[76:77], v[138:139], v[74:75]
	v_cvt_pk_bf16_f32 v74, v78, v79
	v_cvt_pk_bf16_f32 v75, v80, v81
	v_pk_mul_f32 v[70:71], v[134:135], v[70:71]
	v_pk_mul_f32 v[66:67], v[66:67], v[82:83] op_sel_hi:[1,0]
	v_pk_mul_f32 v[68:69], v[68:69], v[82:83] op_sel_hi:[1,0]
	v_cvt_pk_bf16_f32 v76, v76, v77
	v_cvt_pk_bf16_f32 v77, v86, v87
	v_mov_b32_e32 v200, v74
	v_mov_b32_e32 v201, v75
	v_mov_b32_e32 v202, v76
	v_mov_b32_e32 v203, v77
	v_lshl_add_u64 v[216:217], v[84:85], 0, v[218:219]
	v_pk_mul_f32 v[72:73], v[72:73], v[82:83] op_sel_hi:[1,0]
	s_nop 0
	v_pk_mul_f32 v[74:75], v[132:133], v[68:69]
	v_pk_mul_f32 v[68:69], v[130:131], v[66:67]
	v_cvt_pk_bf16_f32 v66, v70, v71
	v_mul_f32_e32 v70, v63, v63
	v_mul_f32_e32 v71, v65, v65
	v_pk_mul_f32 v[72:73], v[136:137], v[72:73]
	v_fmac_f32_e32 v70, v62, v62
	v_fmac_f32_e32 v71, v64, v64
	v_cvt_pk_bf16_f32 v67, v72, v73
	v_add_f32_e32 v70, v70, v71
	v_mul_f32_e32 v71, v59, v59
	v_mul_f32_e32 v72, v61, v61
	v_fmac_f32_e32 v71, v58, v58
	v_fmac_f32_e32 v72, v60, v60
	v_add_f32_e32 v71, v71, v72
	v_add_f32_e32 v70, v70, v71
	v_mul_f32_e32 v71, v55, v55
	v_mul_f32_e32 v72, v57, v57
	v_fmac_f32_e32 v71, v54, v54
	v_fmac_f32_e32 v72, v56, v56
	v_add_f32_e32 v71, v71, v72
	v_add_f32_e32 v70, v70, v71
	v_mul_f32_e32 v71, v51, v51
	v_mul_f32_e32 v72, v53, v53
	v_fmac_f32_e32 v71, v50, v50
	v_fmac_f32_e32 v72, v52, v52
	v_add_f32_e32 v71, v71, v72
	v_add_f32_e32 v70, v70, v71
	v_mov_b32_e32 v71, v70
	s_nop 1
	v_permlane16_swap_b32_e32 v70, v71
	v_add_f32_e32 v70, v70, v71
	v_mov_b32_e32 v71, v70
	s_nop 1
	v_permlane32_swap_b32_e32 v70, v71
	v_add_f32_e32 v70, v70, v71
	v_fmamk_f32 v70, v70, 0x3c800000, v188
	v_mul_f32_e32 v71, 0x4b800000, v70
	v_cmp_gt_f32_e32 vcc, s91, v70
	v_cvt_pk_bf16_f32 v68, v68, v69
	v_cvt_pk_bf16_f32 v69, v74, v75
	v_mov_b32_dpp v212, v200 quad_perm:[1,0,3,2] row_mask:0xf bank_mask:0xf
	v_mov_b32_dpp v213, v201 quad_perm:[1,0,3,2] row_mask:0xf bank_mask:0xf
	v_mov_b32_dpp v214, v202 quad_perm:[1,0,3,2] row_mask:0xf bank_mask:0xf
	v_mov_b32_dpp v215, v203 quad_perm:[1,0,3,2] row_mask:0xf bank_mask:0xf
	v_mov_b32_dpp v204, v66 quad_perm:[1,0,3,2] row_mask:0xf bank_mask:0xf
	v_mov_b32_dpp v205, v67 quad_perm:[1,0,3,2] row_mask:0xf bank_mask:0xf
	v_mov_b32_dpp v206, v68 quad_perm:[1,0,3,2] row_mask:0xf bank_mask:0xf
	v_mov_b32_dpp v207, v69 quad_perm:[1,0,3,2] row_mask:0xf bank_mask:0xf
	v_cndmask_b32_e64 v212, v66, v212, s[4:5]
	v_cndmask_b32_e64 v213, v67, v213, s[4:5]
	v_cndmask_b32_e64 v214, v68, v214, s[4:5]
	v_cndmask_b32_e64 v215, v69, v215, s[4:5]
	v_cndmask_b32_e64 v208, v204, v200, s[4:5]
	v_cndmask_b32_e64 v209, v205, v201, s[4:5]
	v_cndmask_b32_e64 v210, v206, v202, s[4:5]
	v_cndmask_b32_e64 v211, v207, v203, s[4:5]
	global_store_dwordx4 v[216:217], v[208:211], off
	global_store_dwordx4 v[216:217], v[212:215], off offset:1024
	s_nop 0
	v_cndmask_b32_e32 v70, v70, v71, vcc
	v_rsq_f32_e32 v70, v70
	v_lshl_add_u64 v[68:69], v[174:175], 0, s[16:17]
	v_mul_f32_e32 v66, 0x45800000, v70
	v_cndmask_b32_e32 v66, v70, v66, vcc
	v_mul_f32_e32 v66, v178, v66
	v_pk_mul_f32 v[62:63], v[62:63], v[66:67] op_sel_hi:[1,0]
	v_pk_mul_f32 v[58:59], v[58:59], v[66:67] op_sel_hi:[1,0]
; __device__ __forceinline__ unsigned cvt_pk_bf16(float lo, float hi) { unsigned r; asm volatile("v_cvt_pk_bf16_f32 %0, %1, %2" : "=v"(r) : "v"(lo), "v"(hi)); return r; }
;     __device__ __forceinline__ void operator()(const f32x4 (&acc)[2][2][4][2], const pg8::Unit& u, int wr, int wc, int fr, int fq) const {
;     ...
;         if (sec <= 1) {
;             const float* gn = sec == 0 ? qg : kg; const float osc = sec == 0 ? 0.125f * LOG2E : 1.f;
;             f32x4 g[2][2];
; #pragma unroll
;             for (int bj = 0; bj < 2; ++bj)
; #pragma unroll
;                 for (int n = 0; n < 2; ++n) g[bj][n] = *(const f32x4*)(gn + 32 * bj + 8 * fq + 4 * n);
;             const int col0 = 256 * half + 64 * wc + 8 * fq;
; #pragma unroll
;             for (int ai = 0; ai < 2; ++ai)
; #pragma unroll
;                 for (int m = 0; m < 4; ++m) {
;                     float ss = 0.f;
; #pragma unroll
;                     for (int bj = 0; bj < 2; ++bj)
; #pragma unroll
;                         for (int n = 0; n < 2; ++n) { const f32x4 x = acc[ai][bj][m][n]; ss += (x[0] * x[0] + x[1] * x[1]) + (x[2] * x[2] + x[3] * x[3]); }
;                     ss = row4_sum(ss);
;                     const float r = rsqrtf(ss * (1.f / 64.f) + EPS) * osc;
;                     bf16_t* rowp = base + (size_t)(row0 + ai * 128 + m * 16) * 512 + col0;
; #pragma unroll
;                     for (int bj = 0; bj < 2; ++bj) { const f32x4 v0 = acc[ai][bj][m][0] * r * g[bj][0], v1 = acc[ai][bj][m][1] * r * g[bj][1];
;                         u32x4 w; w.x = cvt_pk_bf16(v0[0], v0[1]); w.y = cvt_pk_bf16(v0[2], v0[3]); w.z = cvt_pk_bf16(v1[0], v1[1]); w.w = cvt_pk_bf16(v1[2], v1[3]);
;                         *(u32x4*)(rowp + 32 * bj) = w; }
;                 }
	v_pk_mul_f32 v[62:63], v[142:143], v[62:63]
	v_pk_mul_f32 v[60:61], v[60:61], v[66:67] op_sel_hi:[1,0]
	v_pk_mul_f32 v[64:65], v[64:65], v[66:67] op_sel_hi:[1,0]
	v_pk_mul_f32 v[70:71], v[140:141], v[60:61]
	v_pk_mul_f32 v[60:61], v[138:139], v[58:59]
	v_cvt_pk_bf16_f32 v58, v62, v63
	v_add_co_u32_e32 v62, vcc, s87, v174
	v_pk_mul_f32 v[54:55], v[54:55], v[66:67] op_sel_hi:[1,0]
	v_pk_mul_f32 v[64:65], v[144:145], v[64:65]
	v_addc_co_u32_e32 v63, vcc, 0, v175, vcc
	v_cvt_pk_bf16_f32 v59, v64, v65
	v_pk_mul_f32 v[54:55], v[134:135], v[54:55]
	v_pk_mul_f32 v[50:51], v[50:51], v[66:67] op_sel_hi:[1,0]
	v_pk_mul_f32 v[52:53], v[52:53], v[66:67] op_sel_hi:[1,0]
	v_cvt_pk_bf16_f32 v60, v60, v61
	v_cvt_pk_bf16_f32 v61, v70, v71
	v_mov_b32_e32 v200, v58
	v_mov_b32_e32 v201, v59
	v_mov_b32_e32 v202, v60
	v_mov_b32_e32 v203, v61
	v_lshl_add_u64 v[216:217], v[62:63], 0, v[218:219]
	v_pk_mul_f32 v[56:57], v[56:57], v[66:67] op_sel_hi:[1,0]
	s_nop 0
	v_pk_mul_f32 v[58:59], v[132:133], v[52:53]
	v_pk_mul_f32 v[52:53], v[130:131], v[50:51]
	v_cvt_pk_bf16_f32 v50, v54, v55
	v_mul_f32_e32 v54, v47, v47
	v_mul_f32_e32 v55, v49, v49
	v_pk_mul_f32 v[56:57], v[136:137], v[56:57]
	v_fmac_f32_e32 v54, v46, v46
	v_fmac_f32_e32 v55, v48, v48
	v_cvt_pk_bf16_f32 v51, v56, v57
	v_add_f32_e32 v54, v54, v55
	v_mul_f32_e32 v55, v43, v43
	v_mul_f32_e32 v56, v45, v45
	v_fmac_f32_e32 v55, v42, v42
	v_fmac_f32_e32 v56, v44, v44
	v_add_f32_e32 v55, v55, v56
	v_add_f32_e32 v54, v54, v55
	v_mul_f32_e32 v55, v39, v39
	v_mul_f32_e32 v56, v41, v41
	v_fmac_f32_e32 v55, v38, v38
	v_fmac_f32_e32 v56, v40, v40
	v_add_f32_e32 v55, v55, v56
	v_add_f32_e32 v54, v54, v55
	v_mul_f32_e32 v55, v35, v35
	v_mul_f32_e32 v56, v37, v37
	v_fmac_f32_e32 v55, v34, v34
	v_fmac_f32_e32 v56, v36, v36
	v_add_f32_e32 v55, v55, v56
	v_add_f32_e32 v54, v54, v55
	v_mov_b32_e32 v55, v54
	s_nop 1
	v_permlane16_swap_b32_e32 v54, v55
	v_add_f32_e32 v54, v54, v55
	v_mov_b32_e32 v55, v54
	s_nop 1
	v_permlane32_swap_b32_e32 v54, v55
	v_add_f32_e32 v54, v54, v55
	v_fmamk_f32 v54, v54, 0x3c800000, v188
	v_mul_f32_e32 v55, 0x4b800000, v54
	v_cmp_gt_f32_e32 vcc, s91, v54
	v_cvt_pk_bf16_f32 v52, v52, v53
	v_cvt_pk_bf16_f32 v53, v58, v59
	v_mov_b32_dpp v212, v200 quad_perm:[1,0,3,2] row_mask:0xf bank_mask:0xf
	v_mov_b32_dpp v213, v201 quad_perm:[1,0,3,2] row_mask:0xf bank_mask:0xf
	v_mov_b32_dpp v214, v202 quad_perm:[1,0,3,2] row_mask:0xf bank_mask:0xf
	v_mov_b32_dpp v215, v203 quad_perm:[1,0,3,2] row_mask:0xf bank_mask:0xf
	v_mov_b32_dpp v204, v50 quad_perm:[1,0,3,2] row_mask:0xf bank_mask:0xf
	v_mov_b32_dpp v205, v51 quad_perm:[1,0,3,2] row_mask:0xf bank_mask:0xf
	v_mov_b32_dpp v206, v52 quad_perm:[1,0,3,2] row_mask:0xf bank_mask:0xf
	v_mov_b32_dpp v207, v53 quad_perm:[1,0,3,2] row_mask:0xf bank_mask:0xf
	v_cndmask_b32_e64 v212, v50, v212, s[4:5]
	v_cndmask_b32_e64 v213, v51, v213, s[4:5]
	v_cndmask_b32_e64 v214, v52, v214, s[4:5]
	v_cndmask_b32_e64 v215, v53, v215, s[4:5]
	v_cndmask_b32_e64 v208, v204, v200, s[4:5]
	v_cndmask_b32_e64 v209, v205, v201, s[4:5]
	v_cndmask_b32_e64 v210, v206, v202, s[4:5]
	v_cndmask_b32_e64 v211, v207, v203, s[4:5]
	global_store_dwordx4 v[216:217], v[208:211], off
	global_store_dwordx4 v[216:217], v[212:215], off offset:1024
	s_nop 0
	v_cndmask_b32_e32 v54, v54, v55, vcc
	v_rsq_f32_e32 v54, v54
	v_lshl_add_u64 v[52:53], v[174:175], 0, s[18:19]
	v_mul_f32_e32 v50, 0x45800000, v54
	v_cndmask_b32_e32 v50, v54, v50, vcc
	v_mul_f32_e32 v50, v178, v50
	v_pk_mul_f32 v[46:47], v[46:47], v[50:51] op_sel_hi:[1,0]
	v_pk_mul_f32 v[42:43], v[42:43], v[50:51] op_sel_hi:[1,0]
	v_pk_mul_f32 v[46:47], v[142:143], v[46:47]
	v_pk_mul_f32 v[44:45], v[44:45], v[50:51] op_sel_hi:[1,0]
	v_pk_mul_f32 v[48:49], v[48:49], v[50:51] op_sel_hi:[1,0]
	v_pk_mul_f32 v[54:55], v[140:141], v[44:45]
	v_pk_mul_f32 v[44:45], v[138:139], v[42:43]
	v_cvt_pk_bf16_f32 v42, v46, v47
	v_add_co_u32_e32 v46, vcc, s88, v174
	v_pk_mul_f32 v[38:39], v[38:39], v[50:51] op_sel_hi:[1,0]
	v_pk_mul_f32 v[48:49], v[144:145], v[48:49]
	v_addc_co_u32_e32 v47, vcc, 0, v175, vcc
	v_cvt_pk_bf16_f32 v43, v48, v49
	v_pk_mul_f32 v[38:39], v[134:135], v[38:39]
	v_pk_mul_f32 v[34:35], v[34:35], v[50:51] op_sel_hi:[1,0]
	v_pk_mul_f32 v[36:37], v[36:37], v[50:51] op_sel_hi:[1,0]
	v_cvt_pk_bf16_f32 v44, v44, v45
	v_cvt_pk_bf16_f32 v45, v54, v55
	v_mov_b32_e32 v200, v42
	v_mov_b32_e32 v201, v43
	v_mov_b32_e32 v202, v44
	v_mov_b32_e32 v203, v45
	v_lshl_add_u64 v[216:217], v[46:47], 0, v[218:219]
	v_pk_mul_f32 v[40:41], v[40:41], v[50:51] op_sel_hi:[1,0]
	s_nop 0
	v_pk_mul_f32 v[42:43], v[132:133], v[36:37]
	v_pk_mul_f32 v[36:37], v[130:131], v[34:35]
	v_cvt_pk_bf16_f32 v34, v38, v39
	v_mul_f32_e32 v38, v31, v31
	v_mul_f32_e32 v39, v33, v33
	v_pk_mul_f32 v[40:41], v[136:137], v[40:41]
	v_fmac_f32_e32 v38, v30, v30
	v_fmac_f32_e32 v39, v32, v32
	v_cvt_pk_bf16_f32 v35, v40, v41
	v_add_f32_e32 v38, v38, v39
	v_mul_f32_e32 v39, v27, v27
	v_mul_f32_e32 v40, v29, v29
	v_fmac_f32_e32 v39, v26, v26
	v_fmac_f32_e32 v40, v28, v28
	v_add_f32_e32 v39, v39, v40
	v_add_f32_e32 v38, v38, v39
	v_mul_f32_e32 v39, v23, v23
	v_mul_f32_e32 v40, v25, v25
	v_fmac_f32_e32 v39, v22, v22
	v_fmac_f32_e32 v40, v24, v24
	v_add_f32_e32 v39, v39, v40
	v_add_f32_e32 v38, v38, v39
	v_mul_f32_e32 v39, v19, v19
	v_mul_f32_e32 v40, v21, v21
	v_fmac_f32_e32 v39, v18, v18
	v_fmac_f32_e32 v40, v20, v20
	v_add_f32_e32 v39, v39, v40
	v_add_f32_e32 v38, v38, v39
	v_mov_b32_e32 v39, v38
	s_nop 1
	v_permlane16_swap_b32_e32 v38, v39
	v_add_f32_e32 v38, v38, v39
	v_mov_b32_e32 v39, v38
	s_nop 1
	v_permlane32_swap_b32_e32 v38, v39
	v_add_f32_e32 v38, v38, v39
	v_fmamk_f32 v38, v38, 0x3c800000, v188
; __device__ __forceinline__ unsigned cvt_pk_bf16(float lo, float hi) { unsigned r; asm volatile("v_cvt_pk_bf16_f32 %0, %1, %2" : "=v"(r) : "v"(lo), "v"(hi)); return r; }
;     __device__ __forceinline__ void operator()(const f32x4 (&acc)[2][2][4][2], const pg8::Unit& u, int wr, int wc, int fr, int fq) const {
;     ...
;         if (sec <= 1) {
;             const float* gn = sec == 0 ? qg : kg; const float osc = sec == 0 ? 0.125f * LOG2E : 1.f;
;             f32x4 g[2][2];
; #pragma unroll
;             for (int bj = 0; bj < 2; ++bj)
; #pragma unroll
;                 for (int n = 0; n < 2; ++n) g[bj][n] = *(const f32x4*)(gn + 32 * bj + 8 * fq + 4 * n);
;             const int col0 = 256 * half + 64 * wc + 8 * fq;
; #pragma unroll
;             for (int ai = 0; ai < 2; ++ai)
; #pragma unroll
;                 for (int m = 0; m < 4; ++m) {
;                     float ss = 0.f;
; #pragma unroll
;                     for (int bj = 0; bj < 2; ++bj)
; #pragma unroll
;                         for (int n = 0; n < 2; ++n) { const f32x4 x = acc[ai][bj][m][n]; ss += (x[0] * x[0] + x[1] * x[1]) + (x[2] * x[2] + x[3] * x[3]); }
;                     ss = row4_sum(ss);
;                     const float r = rsqrtf(ss * (1.f / 64.f) + EPS) * osc;
;                     bf16_t* rowp = base + (size_t)(row0 + ai * 128 + m * 16) * 512 + col0;
; #pragma unroll
;                     for (int bj = 0; bj < 2; ++bj) { const f32x4 v0 = acc[ai][bj][m][0] * r * g[bj][0], v1 = acc[ai][bj][m][1] * r * g[bj][1];
;                         u32x4 w; w.x = cvt_pk_bf16(v0[0], v0[1]); w.y = cvt_pk_bf16(v0[2], v0[3]); w.z = cvt_pk_bf16(v1[0], v1[1]); w.w = cvt_pk_bf16(v1[2], v1[3]);
;                         *(u32x4*)(rowp + 32 * bj) = w; }
;                 }
	v_mul_f32_e32 v39, 0x4b800000, v38
	v_cmp_gt_f32_e32 vcc, s91, v38
	v_cvt_pk_bf16_f32 v36, v36, v37
	v_cvt_pk_bf16_f32 v37, v42, v43
	v_mov_b32_dpp v212, v200 quad_perm:[1,0,3,2] row_mask:0xf bank_mask:0xf
	v_mov_b32_dpp v213, v201 quad_perm:[1,0,3,2] row_mask:0xf bank_mask:0xf
	v_mov_b32_dpp v214, v202 quad_perm:[1,0,3,2] row_mask:0xf bank_mask:0xf
	v_mov_b32_dpp v215, v203 quad_perm:[1,0,3,2] row_mask:0xf bank_mask:0xf
	v_mov_b32_dpp v204, v34 quad_perm:[1,0,3,2] row_mask:0xf bank_mask:0xf
	v_mov_b32_dpp v205, v35 quad_perm:[1,0,3,2] row_mask:0xf bank_mask:0xf
	v_mov_b32_dpp v206, v36 quad_perm:[1,0,3,2] row_mask:0xf bank_mask:0xf
	v_mov_b32_dpp v207, v37 quad_perm:[1,0,3,2] row_mask:0xf bank_mask:0xf
	v_cndmask_b32_e64 v212, v34, v212, s[4:5]
	v_cndmask_b32_e64 v213, v35, v213, s[4:5]
	v_cndmask_b32_e64 v214, v36, v214, s[4:5]
	v_cndmask_b32_e64 v215, v37, v215, s[4:5]
	v_cndmask_b32_e64 v208, v204, v200, s[4:5]
	v_cndmask_b32_e64 v209, v205, v201, s[4:5]
	v_cndmask_b32_e64 v210, v206, v202, s[4:5]
	v_cndmask_b32_e64 v211, v207, v203, s[4:5]
	global_store_dwordx4 v[216:217], v[208:211], off
	global_store_dwordx4 v[216:217], v[212:215], off offset:1024
	s_nop 0
	v_cndmask_b32_e32 v38, v38, v39, vcc
	v_rsq_f32_e32 v38, v38
	v_lshl_add_u64 v[36:37], v[174:175], 0, s[20:21]
	v_mul_f32_e32 v34, 0x45800000, v38
	v_cndmask_b32_e32 v34, v38, v34, vcc
	v_mul_f32_e32 v34, v178, v34
	v_pk_mul_f32 v[30:31], v[30:31], v[34:35] op_sel_hi:[1,0]
	v_pk_mul_f32 v[26:27], v[26:27], v[34:35] op_sel_hi:[1,0]
	v_pk_mul_f32 v[30:31], v[142:143], v[30:31]
	v_pk_mul_f32 v[28:29], v[28:29], v[34:35] op_sel_hi:[1,0]
	v_pk_mul_f32 v[32:33], v[32:33], v[34:35] op_sel_hi:[1,0]
	v_pk_mul_f32 v[38:39], v[140:141], v[28:29]
	v_pk_mul_f32 v[28:29], v[138:139], v[26:27]
	v_cvt_pk_bf16_f32 v26, v30, v31
	v_add_co_u32_e32 v30, vcc, s89, v174
	v_pk_mul_f32 v[22:23], v[22:23], v[34:35] op_sel_hi:[1,0]
	v_pk_mul_f32 v[32:33], v[144:145], v[32:33]
	v_addc_co_u32_e32 v31, vcc, 0, v175, vcc
	v_cvt_pk_bf16_f32 v27, v32, v33
	v_pk_mul_f32 v[22:23], v[134:135], v[22:23]
	v_pk_mul_f32 v[18:19], v[18:19], v[34:35] op_sel_hi:[1,0]
	v_pk_mul_f32 v[20:21], v[20:21], v[34:35] op_sel_hi:[1,0]
	v_cvt_pk_bf16_f32 v28, v28, v29
	v_cvt_pk_bf16_f32 v29, v38, v39
	v_mov_b32_e32 v200, v26
	v_mov_b32_e32 v201, v27
	v_mov_b32_e32 v202, v28
	v_mov_b32_e32 v203, v29
	v_lshl_add_u64 v[216:217], v[30:31], 0, v[218:219]
	v_pk_mul_f32 v[24:25], v[24:25], v[34:35] op_sel_hi:[1,0]
	s_nop 0
	v_pk_mul_f32 v[26:27], v[132:133], v[20:21]
	v_pk_mul_f32 v[20:21], v[130:131], v[18:19]
	v_cvt_pk_bf16_f32 v18, v22, v23
	v_mul_f32_e32 v22, v15, v15
	v_mul_f32_e32 v23, v17, v17
	v_pk_mul_f32 v[24:25], v[136:137], v[24:25]
	v_fmac_f32_e32 v22, v14, v14
	v_fmac_f32_e32 v23, v16, v16
	v_cvt_pk_bf16_f32 v19, v24, v25
	v_add_f32_e32 v22, v22, v23
	v_mul_f32_e32 v23, v11, v11
	v_mul_f32_e32 v24, v13, v13
	v_fmac_f32_e32 v23, v10, v10
	v_fmac_f32_e32 v24, v12, v12
	v_add_f32_e32 v23, v23, v24
	v_add_f32_e32 v22, v22, v23
	v_mul_f32_e32 v23, v7, v7
	v_mul_f32_e32 v24, v9, v9
	v_fmac_f32_e32 v23, v6, v6
	v_fmac_f32_e32 v24, v8, v8
	v_add_f32_e32 v23, v23, v24
	v_add_f32_e32 v22, v22, v23
	v_mul_f32_e32 v23, v3, v3
	v_mul_f32_e32 v24, v5, v5
	v_fmac_f32_e32 v23, v2, v2
	v_fmac_f32_e32 v24, v4, v4
	v_add_f32_e32 v23, v23, v24
	v_add_f32_e32 v22, v22, v23
	v_mov_b32_e32 v23, v22
	s_nop 1
	v_permlane16_swap_b32_e32 v22, v23
	v_add_f32_e32 v22, v22, v23
	v_mov_b32_e32 v23, v22
	s_nop 1
	v_permlane32_swap_b32_e32 v22, v23
	v_add_f32_e32 v22, v22, v23
	v_fmamk_f32 v22, v22, 0x3c800000, v188
	v_mul_f32_e32 v23, 0x4b800000, v22
	v_cmp_gt_f32_e32 vcc, s91, v22
	v_cvt_pk_bf16_f32 v20, v20, v21
	v_cvt_pk_bf16_f32 v21, v26, v27
; __device__ __forceinline__ unsigned cvt_pk_bf16(float lo, float hi) { unsigned r; asm volatile("v_cvt_pk_bf16_f32 %0, %1, %2" : "=v"(r) : "v"(lo), "v"(hi)); return r; }
;     __device__ __forceinline__ void operator()(const f32x4 (&acc)[2][2][4][2], const pg8::Unit& u, int wr, int wc, int fr, int fq) const {
;     ...
;         if (sec <= 1) {
;             const float* gn = sec == 0 ? qg : kg; const float osc = sec == 0 ? 0.125f * LOG2E : 1.f;
;             f32x4 g[2][2];
; #pragma unroll
;             for (int bj = 0; bj < 2; ++bj)
; #pragma unroll
;                 for (int n = 0; n < 2; ++n) g[bj][n] = *(const f32x4*)(gn + 32 * bj + 8 * fq + 4 * n);
;             const int col0 = 256 * half + 64 * wc + 8 * fq;
; #pragma unroll
;             for (int ai = 0; ai < 2; ++ai)
; #pragma unroll
;                 for (int m = 0; m < 4; ++m) {
;                     float ss = 0.f;
; #pragma unroll
;                     for (int bj = 0; bj < 2; ++bj)
; #pragma unroll
;                         for (int n = 0; n < 2; ++n) { const f32x4 x = acc[ai][bj][m][n]; ss += (x[0] * x[0] + x[1] * x[1]) + (x[2] * x[2] + x[3] * x[3]); }
;                     ss = row4_sum(ss);
;                     const float r = rsqrtf(ss * (1.f / 64.f) + EPS) * osc;
;                     bf16_t* rowp = base + (size_t)(row0 + ai * 128 + m * 16) * 512 + col0;
; #pragma unroll
;                     for (int bj = 0; bj < 2; ++bj) { const f32x4 v0 = acc[ai][bj][m][0] * r * g[bj][0], v1 = acc[ai][bj][m][1] * r * g[bj][1];
;                         u32x4 w; w.x = cvt_pk_bf16(v0[0], v0[1]); w.y = cvt_pk_bf16(v0[2], v0[3]); w.z = cvt_pk_bf16(v1[0], v1[1]); w.w = cvt_pk_bf16(v1[2], v1[3]);
;                         *(u32x4*)(rowp + 32 * bj) = w; }
;                 }
	v_mov_b32_dpp v212, v200 quad_perm:[1,0,3,2] row_mask:0xf bank_mask:0xf
	v_mov_b32_dpp v213, v201 quad_perm:[1,0,3,2] row_mask:0xf bank_mask:0xf
	v_mov_b32_dpp v214, v202 quad_perm:[1,0,3,2] row_mask:0xf bank_mask:0xf
	v_mov_b32_dpp v215, v203 quad_perm:[1,0,3,2] row_mask:0xf bank_mask:0xf
	v_mov_b32_dpp v204, v18 quad_perm:[1,0,3,2] row_mask:0xf bank_mask:0xf
	v_mov_b32_dpp v205, v19 quad_perm:[1,0,3,2] row_mask:0xf bank_mask:0xf
	v_mov_b32_dpp v206, v20 quad_perm:[1,0,3,2] row_mask:0xf bank_mask:0xf
	v_mov_b32_dpp v207, v21 quad_perm:[1,0,3,2] row_mask:0xf bank_mask:0xf
	v_cndmask_b32_e64 v212, v18, v212, s[4:5]
	v_cndmask_b32_e64 v213, v19, v213, s[4:5]
	v_cndmask_b32_e64 v214, v20, v214, s[4:5]
	v_cndmask_b32_e64 v215, v21, v215, s[4:5]
	v_cndmask_b32_e64 v208, v204, v200, s[4:5]
	v_cndmask_b32_e64 v209, v205, v201, s[4:5]
	v_cndmask_b32_e64 v210, v206, v202, s[4:5]
	v_cndmask_b32_e64 v211, v207, v203, s[4:5]
	global_store_dwordx4 v[216:217], v[208:211], off
	global_store_dwordx4 v[216:217], v[212:215], off offset:1024
	s_nop 0
	v_cndmask_b32_e32 v22, v22, v23, vcc
	v_rsq_f32_e32 v22, v22
	v_lshl_add_u64 v[20:21], v[174:175], 0, s[24:25]
	v_mul_f32_e32 v18, 0x45800000, v22
	v_cndmask_b32_e32 v18, v22, v18, vcc
	v_mul_f32_e32 v18, v178, v18
	v_pk_mul_f32 v[14:15], v[14:15], v[18:19] op_sel_hi:[1,0]
	v_pk_mul_f32 v[10:11], v[10:11], v[18:19] op_sel_hi:[1,0]
	v_pk_mul_f32 v[14:15], v[142:143], v[14:15]
	v_pk_mul_f32 v[12:13], v[12:13], v[18:19] op_sel_hi:[1,0]
	v_pk_mul_f32 v[16:17], v[16:17], v[18:19] op_sel_hi:[1,0]
	v_pk_mul_f32 v[22:23], v[140:141], v[12:13]
	v_pk_mul_f32 v[12:13], v[138:139], v[10:11]
	v_cvt_pk_bf16_f32 v10, v14, v15
	v_add_co_u32_e32 v14, vcc, s90, v174
	v_pk_mul_f32 v[16:17], v[144:145], v[16:17]
	s_nop 0
	v_addc_co_u32_e32 v15, vcc, 0, v175, vcc
	v_cvt_pk_bf16_f32 v11, v16, v17
	v_pk_mul_f32 v[2:3], v[2:3], v[18:19] op_sel_hi:[1,0]
	v_pk_mul_f32 v[4:5], v[4:5], v[18:19] op_sel_hi:[1,0]
	v_cvt_pk_bf16_f32 v12, v12, v13
	v_cvt_pk_bf16_f32 v13, v22, v23
	v_mov_b32_e32 v200, v10
	v_mov_b32_e32 v201, v11
	v_mov_b32_e32 v202, v12
	v_mov_b32_e32 v203, v13
	v_lshl_add_u64 v[216:217], v[14:15], 0, v[218:219]
	v_pk_mul_f32 v[6:7], v[6:7], v[18:19] op_sel_hi:[1,0]
	v_pk_mul_f32 v[8:9], v[8:9], v[18:19] op_sel_hi:[1,0]
	v_pk_mul_f32 v[10:11], v[132:133], v[4:5]
	v_pk_mul_f32 v[4:5], v[130:131], v[2:3]
	v_pk_mul_f32 v[8:9], v[136:137], v[8:9]
	v_pk_mul_f32 v[6:7], v[134:135], v[6:7]
	s_nop 0
	v_cvt_pk_bf16_f32 v2, v6, v7
	v_cvt_pk_bf16_f32 v3, v8, v9
	v_cvt_pk_bf16_f32 v4, v4, v5
	v_cvt_pk_bf16_f32 v5, v10, v11
	v_mov_b32_dpp v212, v200 quad_perm:[1,0,3,2] row_mask:0xf bank_mask:0xf
	v_mov_b32_dpp v213, v201 quad_perm:[1,0,3,2] row_mask:0xf bank_mask:0xf
	v_mov_b32_dpp v214, v202 quad_perm:[1,0,3,2] row_mask:0xf bank_mask:0xf
	v_mov_b32_dpp v215, v203 quad_perm:[1,0,3,2] row_mask:0xf bank_mask:0xf
	v_mov_b32_dpp v204, v2 quad_perm:[1,0,3,2] row_mask:0xf bank_mask:0xf
	v_mov_b32_dpp v205, v3 quad_perm:[1,0,3,2] row_mask:0xf bank_mask:0xf
	v_mov_b32_dpp v206, v4 quad_perm:[1,0,3,2] row_mask:0xf bank_mask:0xf
	v_mov_b32_dpp v207, v5 quad_perm:[1,0,3,2] row_mask:0xf bank_mask:0xf
	v_cndmask_b32_e64 v212, v2, v212, s[4:5]
	v_cndmask_b32_e64 v213, v3, v213, s[4:5]
	v_cndmask_b32_e64 v214, v4, v214, s[4:5]
	v_cndmask_b32_e64 v215, v5, v215, s[4:5]
	v_cndmask_b32_e64 v208, v204, v200, s[4:5]
	v_cndmask_b32_e64 v209, v205, v201, s[4:5]
	v_cndmask_b32_e64 v210, v206, v202, s[4:5]
	v_cndmask_b32_e64 v211, v207, v203, s[4:5]
	global_store_dwordx4 v[216:217], v[208:211], off
	global_store_dwordx4 v[216:217], v[212:215], off offset:1024
	s_andn2_b64 vcc, exec, s[0:1]
	s_mov_b64 s[0:1], -1
	s_cbranch_vccnz .LBB0_158
